# GEMM phase prologues: all 14 stage loads issued up front (first wait vmcnt(8)), last prologue wait+barrier moved behind the first tile header; on top of MFMA accumulator clear
# baseline (speedup 1.0000x reference)
.LBB0_131:
	s_mov_b32 s52, -1
	v_writelane_b32 v248, s52, 41
	s_lshl_b32 s36, s11, 6
	v_mov_b32_e32 v9, v199
	v_readlane_b32 s1, v251, 0
	s_cmp_ge_i32 s1, s36
	v_readfirstlane_b32 s19, v9
	s_mov_b32 s55, s44
	s_cbranch_scc1 .LBB0_151
	v_lshlrev_b32_e32 v0, 4, v9
	s_waitcnt lgkmcnt(0)
	v_add_u32_e32 v1, 0x2000, v0
	v_ashrrev_i32_e32 v2, 31, v1
	v_lshrrev_b32_e32 v2, 22, v2
	v_add_u32_e32 v2, v1, v2
	v_ashrrev_i32_e32 v8, 10, v2
	v_mul_i32_i24_e32 v2, 0x400, v8
	v_sub_u32_e32 v1, v1, v2
	v_lshrrev_b32_e32 v2, 4, v1
	v_bitop3_b32 v1, v2, v1, 32 bitop3:0x6c
	v_ashrrev_i32_e32 v2, 31, v1
	v_lshrrev_b32_e32 v2, 26, v2
	v_add_u32_e32 v2, v1, v2
	v_lshlrev_b32_e32 v3, 3, v8
	v_ashrrev_i32_e32 v10, 6, v2
	v_and_b32_e32 v3, -16, v3
	v_add_u32_e32 v3, v10, v3
	v_and_b32_e32 v4, 3, v10
	s_mov_b32 s2, 0x1fffe0
	v_lshrrev_b32_e32 v5, 2, v3
	v_lshlrev_b32_e32 v6, 1, v3
	v_and_b32_e32 v2, 0xc0, v2
	v_and_or_b32 v4, v3, s2, v4
	v_and_b32_e32 v5, 4, v5
	v_and_b32_e32 v6, 24, v6
	v_sub_u32_e32 v1, v1, v2
	v_or3_b32 v4, v4, v5, v6
	v_lshlrev_b32_e32 v5, 5, v8
	v_ashrrev_i16_sdwa v1, v223, sext(v1) dst_sel:DWORD dst_unused:UNUSED_PAD src0_sel:DWORD src1_sel:BYTE_0
	v_and_b32_e32 v5, 32, v5
	v_bfe_i32 v11, v1, 0, 16
	v_add_lshl_u32 v1, v5, v11, 1
	s_waitcnt vmcnt(0)
	v_lshl_add_u32 v152, v4, 11, v1
	v_lshl_add_u32 v154, v3, 11, v1
	v_bfe_i32 v1, v9, 27, 1
	v_lshrrev_b32_e32 v1, 22, v1
	v_add_u32_e32 v1, v0, v1
	v_and_b32_e32 v1, 0xfffffc00, v1
	v_sub_u32_e32 v0, v0, v1
	v_lshrrev_b32_e32 v1, 4, v0
	v_ashrrev_i32_e32 v2, 31, v9
	v_bitop3_b32 v0, v1, v0, 32 bitop3:0x6c
	v_lshrrev_b32_e32 v2, 26, v2
	v_ashrrev_i32_e32 v1, 31, v0
	v_add_u32_e32 v2, v9, v2
	v_lshrrev_b32_e32 v1, 26, v1
	v_ashrrev_i32_e32 v13, 6, v2
	v_add_u32_e32 v1, v0, v1
	v_lshlrev_b32_e32 v2, 3, v13
	v_ashrrev_i32_e32 v12, 6, v1
	v_and_b32_e32 v2, -16, v2
	v_add_u32_e32 v2, v12, v2
	v_and_b32_e32 v3, 3, v12
	s_ashr_i32 s21, s19, 6
	v_and_or_b32 v3, v2, s2, v3
	s_lshl_b32 s2, s11, 3
	v_readlane_b32 s12, v250, 5
	s_ashr_i32 s20, s19, 8
	s_lshl_b32 s1, s21, 10
	s_or_b32 s3, s2, 1
	v_readlane_b32 s13, v250, 6
	s_and_b64 s[12:13], s[12:13], exec
	v_and_b32_e32 v1, 0xc0, v1
	s_cselect_b32 s12, s3, s2
	s_lshl_b32 s9, s11, 2
	v_sub_u32_e32 v0, v0, v1
	v_cvt_f32_u32_e32 v1, s9
	v_lshrrev_b32_e32 v4, 2, v2
	v_lshlrev_b32_e32 v5, 1, v2
	v_and_b32_e32 v4, 4, v4
	v_and_b32_e32 v5, 24, v5
	v_rcp_iflag_f32_e32 v1, v1
	v_or3_b32 v3, v3, v4, v5
	v_lshlrev_b32_e32 v4, 5, v13
	v_ashrrev_i16_sdwa v0, v223, sext(v0) dst_sel:DWORD dst_unused:UNUSED_PAD src0_sel:DWORD src1_sel:BYTE_0
	v_and_b32_e32 v4, 32, v4
	v_bfe_i32 v14, v0, 0, 16
	v_add_lshl_u32 v0, v4, v14, 1
	v_lshl_add_u32 v196, v3, 11, v0
	v_lshl_add_u32 v156, v2, 11, v0
	v_mul_f32_e32 v0, 0x4f7ffffe, v1
	v_cvt_u32_f32_e32 v0, v0
	v_readlane_b32 s11, v250, 12
	s_mul_i32 s11, s12, s11
	v_readlane_b32 s12, v250, 7
	s_add_i32 s12, s11, s12
	s_sub_i32 s11, 0, s9
	v_readfirstlane_b32 s15, v0
	s_mul_i32 s11, s11, s15
	s_mul_hi_u32 s11, s15, s11
	s_abs_i32 s14, s12
	s_add_i32 s11, s15, s11
	s_mul_hi_u32 s15, s14, s11
	s_mul_i32 s17, s15, s9
	s_sub_i32 s14, s14, s17
	s_ashr_i32 s13, s12, 31
	s_add_i32 s17, s15, 1
	s_sub_i32 s18, s14, s9
	s_cmp_ge_u32 s14, s9
	s_cselect_b32 s15, s17, s15
	s_cselect_b32 s14, s18, s14
	s_add_i32 s17, s15, 1
	s_cmp_ge_u32 s14, s9
	s_cselect_b32 s14, s17, s15
	s_xor_b32 s14, s14, s13
	s_sub_i32 s13, s14, s13
	s_lshl_b32 s14, s13, 2
	s_sub_i32 s15, 64, s14
	s_min_i32 s15, s15, 4
	s_sext_i32_i16 s17, s15
	v_cvt_f32_i32_e32 v0, s17
	s_mul_i32 s13, s13, s9
	s_sub_i32 s22, s12, s13
	s_sext_i32_i16 s12, s22
	v_cvt_f32_i32_e32 v1, s12
	v_rcp_iflag_f32_e32 v2, v0
	s_xor_b32 s12, s12, s17
	s_ashr_i32 s12, s12, 30
	s_or_b32 s17, s12, 1
	v_mul_f32_e32 v2, v1, v2
	v_trunc_f32_e32 v2, v2
	v_fma_f32 v1, -v2, v0, v1
	v_cvt_i32_f32_e32 v2, v2
	v_cmp_ge_f32_e64 s[12:13], |v1|, |v0|
	s_and_b64 s[12:13], s[12:13], exec
	s_cselect_b32 s12, s17, 0
	v_readfirstlane_b32 s13, v2
	s_add_i32 s18, s13, s12
	s_mul_i32 s12, s18, s15
	s_sub_i32 s12, s22, s12
	s_sext_i32_i16 s12, s12
	s_add_i32 s34, s14, s12
	s_ashr_i32 s35, s34, 31
	s_bfe_i64 s[14:15], s[18:19], 0x100000
	s_lshl_b64 s[12:13], s[34:35], 19
	s_lshl_b64 s[14:15], s[14:15], 19
	s_add_u32 s44, s6, s14
	s_addc_u32 s45, s7, s15
	s_add_i32 s14, s1, 0
	s_add_i32 m0, s14, 0x10000
	v_mov_b32_e32 v153, v197
	global_load_lds_dwordx4 v196, s[44:45]
	s_add_i32 m0, s14, 0x12000
	s_add_u32 s22, s44, 0x40000
	global_load_lds_dwordx4 v152, s[44:45]
	s_addc_u32 s23, s45, 0
	s_add_i32 m0, s14, 0x14000
	v_mov_b32_e32 v157, v197
	global_load_lds_dwordx4 v196, s[22:23]
	s_add_i32 m0, s14, 0x16000
	s_add_u32 s40, s80, s12
	s_addc_u32 s41, s81, s13
	s_add_i32 s15, s14, 0x2000
	global_load_lds_dwordx4 v152, s[22:23]
	s_mov_b32 m0, s14
	s_add_u32 s12, s40, 0x40000
	global_load_lds_dwordx4 v156, s[40:41]
	s_mov_b32 m0, s15
	s_addc_u32 s13, s41, 0
	s_add_i32 s17, s14, 0x4000
	global_load_lds_dwordx4 v154, s[40:41]
	s_mov_b32 m0, s17
	s_add_i32 s26, s14, 0x6000
	global_load_lds_dwordx4 v156, s[12:13]
	s_mov_b32 m0, s26
	v_mov_b32_e32 v155, v197
	global_load_lds_dwordx4 v154, s[12:13]
	s_cmp_eq_u32 s20, 1
	s_mov_b32 s56, s30
	v_lshl_add_u64 v[6:7], s[44:45], 0, v[196:197]
	v_lshl_add_u64 v[4:5], s[44:45], 0, v[152:153]
	v_lshl_add_u64 v[0:1], s[40:41], 0, v[156:157]
	s_cselect_b64 s[12:13], -1, 0
	s_cmp_lg_u32 s20, 1
	v_lshl_add_u64 v[2:3], s[40:41], 0, v[154:155]
	s_add_i32 m0, s14, 0x18000
	v_lshl_add_u64 v[6:7], v[6:7], 0, s[88:89]
	global_load_lds_dwordx4 v[6:7], off
	v_lshl_add_u64 v[4:5], v[4:5], 0, s[88:89]
	s_add_i32 m0, s14, 0x1a000
	s_add_i32 s27, s14, 0x8000
	s_add_i32 s28, s14, 0xa000
	global_load_lds_dwordx4 v[4:5], off
	v_lshl_add_u64 v[0:1], v[0:1], 0, s[88:89]
	s_mov_b32 m0, s27
	s_add_u32 s22, s44, 0x40080
	global_load_lds_dwordx4 v[0:1], off
	v_lshl_add_u64 v[0:1], v[2:3], 0, s[88:89]
	s_mov_b32 m0, s28
	s_addc_u32 s23, s45, 0
	global_load_lds_dwordx4 v[0:1], off
	s_add_i32 m0, s14, 0x1c000
	v_lshl_add_u64 v[0:1], s[22:23], 0, v[196:197]
	global_load_lds_dwordx4 v[0:1], off
	v_lshl_add_u64 v[0:1], s[22:23], 0, v[152:153]
	s_add_i32 m0, s14, 0x1e000
	s_nop 0
	global_load_lds_dwordx4 v[0:1], off
	s_cmp_lg_u32 s20, 1
	s_cbranch_scc1 .LBB0_134
	s_barrier
.LBB0_134:
	s_lshl_b32 s21, s21, 5
	s_and_b32 s21, s21, 0x60
	s_lshl_b32 s24, s20, 13
	s_lshl_b32 s25, s21, 7
	s_waitcnt vmcnt(8)
	s_barrier
	v_bfe_u32 v2, v9, 4, 2
	v_and_b32_e32 v1, 15, v9
	v_lshlrev_b32_e32 v0, 4, v2
	v_lshlrev_b32_e32 v3, 2, v9
	v_lshl_or_b32 v184, s20, 6, v1
	v_lshl_or_b32 v1, v1, 6, v0
	v_and_b32_e32 v3, 32, v3
	v_readlane_b32 s22, v249, 56
	v_bitop3_b32 v4, v1, s24, v3 bitop3:0xde
	v_bitop3_b32 v185, v1, s25, v3 bitop3:0xde
	v_mov_b32_e32 v1, v197
	v_readlane_b32 s23, v249, 57
	s_cmpk_lt_u32 s19, 0x100
	s_sext_i32_i16 s33, s18
	v_lshl_add_u64 v[158:159], s[22:23], 0, v[0:1]
	v_lshlrev_b32_e32 v0, 14, v13
	v_and_b32_e32 v0, 0xffff8000, v0
	v_lshl_add_u32 v0, v12, 11, v0
	v_and_b32_e32 v1, 1, v13
	v_lshl_or_b32 v0, v1, 6, v0
	v_lshl_add_u32 v160, v14, 1, v0
	v_lshlrev_b32_e32 v0, 14, v8
	v_and_b32_e32 v0, 0xffff8000, v0
	v_lshl_add_u32 v0, v10, 11, v0
	v_and_b32_e32 v1, 1, v8
	v_lshl_or_b32 v0, v1, 6, v0
	s_cselect_b64 s[18:19], -1, 0
	v_lshl_or_b32 v186, v2, 3, s21
	v_mov_b32_e32 v161, v197
	v_lshl_add_u32 v162, v11, 1, v0
	v_mov_b32_e32 v163, v197
	s_mov_b32 s29, 0
	v_add_u32_e32 v187, 0, v4
	v_mov_b64_e32 v[164:165], s[36:37]
	s_branch .LBB0_137

.LBB0_139:
	s_ashr_i32 s23, s22, 31
	s_lshl_b64 s[24:25], s[22:23], 19
	s_add_u32 s24, s80, s24
	s_addc_u32 s25, s81, s25
	s_and_b64 s[30:31], s[42:43], exec
	s_cselect_b32 s23, s25, s41
	s_cselect_b32 s35, s24, s40
	s_ashr_i32 s21, s20, 31
	s_lshl_b64 s[30:31], s[20:21], 19
	s_add_u32 s30, s6, s30
	s_addc_u32 s31, s7, s31
	s_and_b64 s[46:47], s[42:43], exec
	s_cselect_b32 s21, s31, s45
	s_cselect_b32 s36, s30, s44
	s_add_u32 s40, s40, 0x40080
	s_addc_u32 s41, s41, 0
	s_add_u32 s48, s44, 0x100
	v_mov_b32_e32 v228, 0
	v_mov_b32_e32 v229, 0
	v_mov_b32_e32 v230, 0
	v_mov_b32_e32 v231, 0
	s_addc_u32 s49, s45, 0
	s_mov_b32 s50, -2
	v_mfma_f32_32x32x16_bf16 v[0:15], v[228:231], v[228:231], 0
	v_mfma_f32_32x32x16_bf16 v[16:31], v[228:231], v[228:231], 0
	v_mfma_f32_32x32x16_bf16 v[32:47], v[228:231], v[228:231], 0
	v_mfma_f32_32x32x16_bf16 v[48:63], v[228:231], v[228:231], 0
	v_mfma_f32_32x32x16_bf16 v[64:79], v[228:231], v[228:231], 0
	v_mfma_f32_32x32x16_bf16 v[80:95], v[228:231], v[228:231], 0
	v_mfma_f32_32x32x16_bf16 v[96:111], v[228:231], v[228:231], 0
	v_mfma_f32_32x32x16_bf16 v[112:127], v[228:231], v[228:231], 0
	s_cmp_lg_u32 s29, 1
	s_cbranch_scc1 .Lfw_0
	s_waitcnt vmcnt(6)
	s_barrier
.Lfw_0:
.LBB0_140:
	s_add_u32 s44, s40, 0xfffc0080
	s_addc_u32 s45, s41, -1
	s_add_i32 s51, 0, 0x10000
	s_cmp_eq_u32 s50, 12
	s_cselect_b32 s47, s23, s45
	s_cselect_b32 s46, s35, s44
	s_cselect_b32 s45, s21, s49
	s_cselect_b32 s44, s36, s48
	s_add_i32 s54, 0, 0x14000
	v_add_u32_e32 v140, s51, v185
	v_add_u32_e32 v170, s54, v185
	ds_read_b128 v[128:131], v140
	ds_read_b128 v[132:135], v140 offset:1024
	ds_read_b128 v[136:139], v140 offset:2048
	ds_read_b128 v[140:143], v140 offset:3072
	ds_read_b128 v[144:147], v170
	ds_read_b128 v[148:151], v170 offset:1024
	ds_read_b128 v[166:169], v170 offset:2048
	ds_read_b128 v[170:173], v170 offset:3072
	v_lshl_add_u64 v[182:183], s[40:41], 0, v[160:161]
	s_add_i32 m0, s14, 0xc000
	ds_read_b128 v[174:177], v187
	ds_read_b128 v[178:181], v187 offset:1024
	ds_read_b128 v[188:191], v187 offset:2048
	ds_read_b128 v[192:195], v187 offset:3072
	ds_read_b128 v[204:207], v187 offset:4096
	ds_read_b128 v[208:211], v187 offset:5120
	ds_read_b128 v[212:215], v187 offset:6144
	ds_read_b128 v[216:219], v187 offset:7168
	global_load_lds_dwordx4 v[182:183], off
	v_lshl_add_u64 v[182:183], s[40:41], 0, v[162:163]
	s_add_i32 m0, s14, 0xe000
	s_nop 0
	global_load_lds_dwordx4 v[182:183], off
	s_waitcnt vmcnt(8)
	s_waitcnt lgkmcnt(0)
	s_barrier
	s_setprio 1
	s_waitcnt lgkmcnt(0)
	v_mfma_f32_16x16x32_bf16 v[120:123], v[128:131], v[174:177], v[120:123]
	v_mfma_f32_16x16x32_bf16 v[112:115], v[136:139], v[174:177], v[112:115]
	v_mfma_f32_16x16x32_bf16 v[104:107], v[128:131], v[188:191], v[104:107]
	v_mfma_f32_16x16x32_bf16 v[96:99], v[136:139], v[188:191], v[96:99]
	v_mfma_f32_16x16x32_bf16 v[88:91], v[128:131], v[204:207], v[88:91]
	v_mfma_f32_16x16x32_bf16 v[80:83], v[136:139], v[204:207], v[80:83]
	v_mfma_f32_16x16x32_bf16 v[72:75], v[128:131], v[212:215], v[72:75]
	v_mfma_f32_16x16x32_bf16 v[64:67], v[136:139], v[212:215], v[64:67]
	v_mfma_f32_16x16x32_bf16 v[120:123], v[132:135], v[178:181], v[120:123]
	v_mfma_f32_16x16x32_bf16 v[112:115], v[140:143], v[178:181], v[112:115]
	v_mfma_f32_16x16x32_bf16 v[104:107], v[132:135], v[192:195], v[104:107]
	v_mfma_f32_16x16x32_bf16 v[96:99], v[140:143], v[192:195], v[96:99]
	v_mfma_f32_16x16x32_bf16 v[88:91], v[132:135], v[208:211], v[88:91]
	v_mfma_f32_16x16x32_bf16 v[80:83], v[140:143], v[208:211], v[80:83]
	v_mfma_f32_16x16x32_bf16 v[72:75], v[132:135], v[216:219], v[72:75]
	v_mfma_f32_16x16x32_bf16 v[64:67], v[140:143], v[216:219], v[64:67]
	s_setprio 0
	s_setprio 1
	v_mfma_f32_16x16x32_bf16 v[124:127], v[144:147], v[174:177], v[124:127]
	v_mfma_f32_16x16x32_bf16 v[116:119], v[166:169], v[174:177], v[116:119]
	v_mfma_f32_16x16x32_bf16 v[108:111], v[144:147], v[188:191], v[108:111]
	v_mfma_f32_16x16x32_bf16 v[100:103], v[166:169], v[188:191], v[100:103]
	v_mfma_f32_16x16x32_bf16 v[92:95], v[144:147], v[204:207], v[92:95]
	v_mfma_f32_16x16x32_bf16 v[84:87], v[166:169], v[204:207], v[84:87]
	v_mfma_f32_16x16x32_bf16 v[76:79], v[144:147], v[212:215], v[76:79]
	v_mfma_f32_16x16x32_bf16 v[68:71], v[166:169], v[212:215], v[68:71]
	v_mfma_f32_16x16x32_bf16 v[124:127], v[148:151], v[178:181], v[124:127]
	v_mfma_f32_16x16x32_bf16 v[116:119], v[170:173], v[178:181], v[116:119]
	v_mfma_f32_16x16x32_bf16 v[108:111], v[148:151], v[192:195], v[108:111]
	v_mfma_f32_16x16x32_bf16 v[100:103], v[170:173], v[192:195], v[100:103]
	v_mfma_f32_16x16x32_bf16 v[92:95], v[148:151], v[208:211], v[92:95]
	v_mfma_f32_16x16x32_bf16 v[84:87], v[170:173], v[208:211], v[84:87]
	v_mfma_f32_16x16x32_bf16 v[76:79], v[148:151], v[216:219], v[76:79]
	v_mfma_f32_16x16x32_bf16 v[68:71], v[170:173], v[216:219], v[68:71]
	s_setprio 0
	s_barrier
	s_add_i32 s51, s51, s1
	v_lshl_add_u64 v[182:183], s[44:45], 0, v[196:197]
	s_mov_b32 m0, s51
	ds_read_b128 v[174:177], v187 offset:16384
	ds_read_b128 v[178:181], v187 offset:17408
	ds_read_b128 v[188:191], v187 offset:18432
	ds_read_b128 v[192:195], v187 offset:19456
	ds_read_b128 v[204:207], v187 offset:20480
	ds_read_b128 v[208:211], v187 offset:21504
	ds_read_b128 v[212:215], v187 offset:22528
	ds_read_b128 v[216:219], v187 offset:23552
	global_load_lds_dwordx4 v[182:183], off
	s_add_i32 m0, s51, 0x2000
	s_add_u32 s52, s44, 0x40000
	v_lshl_add_u64 v[220:221], s[44:45], 0, v[152:153]
	s_addc_u32 s53, s45, 0
	s_add_i32 s51, s54, s1
	global_load_lds_dwordx4 v[220:221], off
	v_lshl_add_u64 v[226:227], s[52:53], 0, v[196:197]
	s_mov_b32 m0, s51
	v_lshl_add_u64 v[228:229], s[46:47], 0, v[154:155]
	global_load_lds_dwordx4 v[226:227], off
	v_lshl_add_u64 v[226:227], s[52:53], 0, v[152:153]
	s_add_i32 m0, s51, 0x2000
	s_nop 0
	global_load_lds_dwordx4 v[226:227], off
	v_lshl_add_u64 v[226:227], s[46:47], 0, v[156:157]
	s_mov_b32 m0, s14
	s_nop 0
	global_load_lds_dwordx4 v[226:227], off
	s_mov_b32 m0, s15
	s_nop 0
	global_load_lds_dwordx4 v[228:229], off
	s_waitcnt vmcnt(8)
	s_waitcnt lgkmcnt(0)
	s_barrier
	s_setprio 1
	s_waitcnt lgkmcnt(0)
	v_mfma_f32_16x16x32_bf16 v[56:59], v[128:131], v[174:177], v[56:59]
	v_mfma_f32_16x16x32_bf16 v[48:51], v[136:139], v[174:177], v[48:51]
	v_mfma_f32_16x16x32_bf16 v[40:43], v[128:131], v[188:191], v[40:43]
	v_mfma_f32_16x16x32_bf16 v[32:35], v[136:139], v[188:191], v[32:35]
	v_mfma_f32_16x16x32_bf16 v[24:27], v[128:131], v[204:207], v[24:27]
	v_mfma_f32_16x16x32_bf16 v[16:19], v[136:139], v[204:207], v[16:19]
	v_mfma_f32_16x16x32_bf16 v[8:11], v[128:131], v[212:215], v[8:11]
	v_mfma_f32_16x16x32_bf16 v[0:3], v[136:139], v[212:215], v[0:3]
	v_mfma_f32_16x16x32_bf16 v[56:59], v[132:135], v[178:181], v[56:59]
	v_mfma_f32_16x16x32_bf16 v[48:51], v[140:143], v[178:181], v[48:51]
	v_mfma_f32_16x16x32_bf16 v[40:43], v[132:135], v[192:195], v[40:43]
	v_mfma_f32_16x16x32_bf16 v[32:35], v[140:143], v[192:195], v[32:35]
	v_mfma_f32_16x16x32_bf16 v[24:27], v[132:135], v[208:211], v[24:27]
	v_mfma_f32_16x16x32_bf16 v[16:19], v[140:143], v[208:211], v[16:19]
	v_mfma_f32_16x16x32_bf16 v[8:11], v[132:135], v[216:219], v[8:11]
	v_mfma_f32_16x16x32_bf16 v[0:3], v[140:143], v[216:219], v[0:3]
	s_setprio 0
	s_setprio 1
	v_mfma_f32_16x16x32_bf16 v[60:63], v[144:147], v[174:177], v[60:63]
	v_mfma_f32_16x16x32_bf16 v[52:55], v[166:169], v[174:177], v[52:55]
	v_mfma_f32_16x16x32_bf16 v[44:47], v[144:147], v[188:191], v[44:47]
	v_mfma_f32_16x16x32_bf16 v[36:39], v[166:169], v[188:191], v[36:39]
	v_mfma_f32_16x16x32_bf16 v[28:31], v[144:147], v[204:207], v[28:31]
	v_mfma_f32_16x16x32_bf16 v[20:23], v[166:169], v[204:207], v[20:23]
	v_mfma_f32_16x16x32_bf16 v[12:15], v[144:147], v[212:215], v[12:15]
	v_mfma_f32_16x16x32_bf16 v[4:7], v[166:169], v[212:215], v[4:7]
	v_mfma_f32_16x16x32_bf16 v[60:63], v[148:151], v[178:181], v[60:63]
	v_mfma_f32_16x16x32_bf16 v[52:55], v[170:173], v[178:181], v[52:55]
	v_mfma_f32_16x16x32_bf16 v[44:47], v[148:151], v[192:195], v[44:47]
	v_mfma_f32_16x16x32_bf16 v[36:39], v[170:173], v[192:195], v[36:39]
	v_mfma_f32_16x16x32_bf16 v[28:31], v[148:151], v[208:211], v[28:31]
	v_mfma_f32_16x16x32_bf16 v[20:23], v[170:173], v[208:211], v[20:23]
	v_mfma_f32_16x16x32_bf16 v[12:15], v[148:151], v[216:219], v[12:15]
	v_mfma_f32_16x16x32_bf16 v[4:7], v[170:173], v[216:219], v[4:7]
	s_setprio 0
	s_barrier
	s_add_i32 s51, 0, 0x18000
	s_add_i32 s52, 0, 0x1c000
	v_add_u32_e32 v140, s51, v185
	v_add_u32_e32 v170, s52, v185
	ds_read_b128 v[128:131], v140
	ds_read_b128 v[132:135], v140 offset:1024
	ds_read_b128 v[136:139], v140 offset:2048
	ds_read_b128 v[140:143], v140 offset:3072
	ds_read_b128 v[144:147], v170
	ds_read_b128 v[148:151], v170 offset:1024
	ds_read_b128 v[166:169], v170 offset:2048
	ds_read_b128 v[170:173], v170 offset:3072
	s_add_u32 s46, s46, 0x40000
	s_addc_u32 s47, s47, 0
	s_mov_b32 m0, s17
	v_lshl_add_u64 v[230:231], s[46:47], 0, v[156:157]
	ds_read_b128 v[174:177], v187 offset:32768
	ds_read_b128 v[178:181], v187 offset:33792
	ds_read_b128 v[188:191], v187 offset:34816
	ds_read_b128 v[192:195], v187 offset:35840
	ds_read_b128 v[204:207], v187 offset:36864
	ds_read_b128 v[208:211], v187 offset:37888
	ds_read_b128 v[212:215], v187 offset:38912
	ds_read_b128 v[216:219], v187 offset:39936
	global_load_lds_dwordx4 v[230:231], off
	v_lshl_add_u64 v[230:231], s[46:47], 0, v[154:155]
	s_mov_b32 m0, s26
	s_nop 0
	global_load_lds_dwordx4 v[230:231], off
	s_waitcnt vmcnt(8)
	s_waitcnt lgkmcnt(0)
	s_barrier
	s_setprio 1
	s_waitcnt lgkmcnt(0)
	v_mfma_f32_16x16x32_bf16 v[120:123], v[128:131], v[174:177], v[120:123]
	v_mfma_f32_16x16x32_bf16 v[112:115], v[136:139], v[174:177], v[112:115]
	v_mfma_f32_16x16x32_bf16 v[104:107], v[128:131], v[188:191], v[104:107]
	v_mfma_f32_16x16x32_bf16 v[96:99], v[136:139], v[188:191], v[96:99]
	v_mfma_f32_16x16x32_bf16 v[88:91], v[128:131], v[204:207], v[88:91]
	v_mfma_f32_16x16x32_bf16 v[80:83], v[136:139], v[204:207], v[80:83]
	v_mfma_f32_16x16x32_bf16 v[72:75], v[128:131], v[212:215], v[72:75]
	v_mfma_f32_16x16x32_bf16 v[64:67], v[136:139], v[212:215], v[64:67]
	v_mfma_f32_16x16x32_bf16 v[120:123], v[132:135], v[178:181], v[120:123]
	v_mfma_f32_16x16x32_bf16 v[112:115], v[140:143], v[178:181], v[112:115]
	v_mfma_f32_16x16x32_bf16 v[104:107], v[132:135], v[192:195], v[104:107]
	v_mfma_f32_16x16x32_bf16 v[96:99], v[140:143], v[192:195], v[96:99]
	v_mfma_f32_16x16x32_bf16 v[88:91], v[132:135], v[208:211], v[88:91]
	v_mfma_f32_16x16x32_bf16 v[80:83], v[140:143], v[208:211], v[80:83]
	v_mfma_f32_16x16x32_bf16 v[72:75], v[132:135], v[216:219], v[72:75]
	v_mfma_f32_16x16x32_bf16 v[64:67], v[140:143], v[216:219], v[64:67]
	s_setprio 0
	s_setprio 1
	v_mfma_f32_16x16x32_bf16 v[124:127], v[144:147], v[174:177], v[124:127]
	v_mfma_f32_16x16x32_bf16 v[116:119], v[166:169], v[174:177], v[116:119]
	v_mfma_f32_16x16x32_bf16 v[108:111], v[144:147], v[188:191], v[108:111]
	v_mfma_f32_16x16x32_bf16 v[100:103], v[166:169], v[188:191], v[100:103]
	v_mfma_f32_16x16x32_bf16 v[92:95], v[144:147], v[204:207], v[92:95]
	v_mfma_f32_16x16x32_bf16 v[84:87], v[166:169], v[204:207], v[84:87]
	v_mfma_f32_16x16x32_bf16 v[76:79], v[144:147], v[212:215], v[76:79]
	v_mfma_f32_16x16x32_bf16 v[68:71], v[166:169], v[212:215], v[68:71]
	v_mfma_f32_16x16x32_bf16 v[124:127], v[148:151], v[178:181], v[124:127]
	v_mfma_f32_16x16x32_bf16 v[116:119], v[170:173], v[178:181], v[116:119]
	v_mfma_f32_16x16x32_bf16 v[108:111], v[148:151], v[192:195], v[108:111]
	v_mfma_f32_16x16x32_bf16 v[100:103], v[170:173], v[192:195], v[100:103]
	v_mfma_f32_16x16x32_bf16 v[92:95], v[148:151], v[208:211], v[92:95]
	v_mfma_f32_16x16x32_bf16 v[84:87], v[170:173], v[208:211], v[84:87]
	v_mfma_f32_16x16x32_bf16 v[76:79], v[148:151], v[216:219], v[76:79]
	v_mfma_f32_16x16x32_bf16 v[68:71], v[170:173], v[216:219], v[68:71]
	s_setprio 0
	s_barrier
	s_add_i32 s46, s51, s1
	v_lshl_add_u64 v[182:183], v[182:183], 0, s[88:89]
	s_mov_b32 m0, s46
	ds_read_b128 v[174:177], v187 offset:49152
	ds_read_b128 v[178:181], v187 offset:50176
	ds_read_b128 v[188:191], v187 offset:51200
	ds_read_b128 v[192:195], v187 offset:52224
	ds_read_b128 v[204:207], v187 offset:53248
	ds_read_b128 v[208:211], v187 offset:54272
	ds_read_b128 v[212:215], v187 offset:55296
	ds_read_b128 v[216:219], v187 offset:56320
	global_load_lds_dwordx4 v[182:183], off
	s_add_i32 m0, s46, 0x2000
	s_add_u32 s44, s44, 0x40080
	v_lshl_add_u64 v[182:183], v[220:221], 0, s[88:89]
	s_addc_u32 s45, s45, 0
	s_add_i32 s46, s52, s1
	global_load_lds_dwordx4 v[182:183], off
	v_lshl_add_u64 v[182:183], s[44:45], 0, v[196:197]
	s_mov_b32 m0, s46
	s_nop 0
	global_load_lds_dwordx4 v[182:183], off
	v_lshl_add_u64 v[182:183], s[44:45], 0, v[152:153]
	s_add_i32 m0, s46, 0x2000
	s_nop 0
	global_load_lds_dwordx4 v[182:183], off
	v_lshl_add_u64 v[182:183], v[226:227], 0, s[88:89]
	s_mov_b32 m0, s27
	s_nop 0
	global_load_lds_dwordx4 v[182:183], off
	v_lshl_add_u64 v[182:183], v[228:229], 0, s[88:89]
	s_mov_b32 m0, s28
	s_nop 0
	global_load_lds_dwordx4 v[182:183], off
	s_waitcnt vmcnt(8)
	s_waitcnt lgkmcnt(0)
	s_barrier
	s_setprio 1
	s_waitcnt lgkmcnt(0)
	v_mfma_f32_16x16x32_bf16 v[56:59], v[128:131], v[174:177], v[56:59]
	v_mfma_f32_16x16x32_bf16 v[48:51], v[136:139], v[174:177], v[48:51]
	v_mfma_f32_16x16x32_bf16 v[40:43], v[128:131], v[188:191], v[40:43]
	v_mfma_f32_16x16x32_bf16 v[32:35], v[136:139], v[188:191], v[32:35]
	v_mfma_f32_16x16x32_bf16 v[24:27], v[128:131], v[204:207], v[24:27]
	v_mfma_f32_16x16x32_bf16 v[16:19], v[136:139], v[204:207], v[16:19]
	v_mfma_f32_16x16x32_bf16 v[8:11], v[128:131], v[212:215], v[8:11]
	v_mfma_f32_16x16x32_bf16 v[0:3], v[136:139], v[212:215], v[0:3]
	v_mfma_f32_16x16x32_bf16 v[56:59], v[132:135], v[178:181], v[56:59]
	v_mfma_f32_16x16x32_bf16 v[48:51], v[140:143], v[178:181], v[48:51]
	v_mfma_f32_16x16x32_bf16 v[40:43], v[132:135], v[192:195], v[40:43]
	v_mfma_f32_16x16x32_bf16 v[32:35], v[140:143], v[192:195], v[32:35]
	v_mfma_f32_16x16x32_bf16 v[24:27], v[132:135], v[208:211], v[24:27]
	v_mfma_f32_16x16x32_bf16 v[16:19], v[140:143], v[208:211], v[16:19]
	v_mfma_f32_16x16x32_bf16 v[8:11], v[132:135], v[216:219], v[8:11]
	v_mfma_f32_16x16x32_bf16 v[0:3], v[140:143], v[216:219], v[0:3]
	s_setprio 0
	s_setprio 1
	v_mfma_f32_16x16x32_bf16 v[60:63], v[144:147], v[174:177], v[60:63]
	v_mfma_f32_16x16x32_bf16 v[52:55], v[166:169], v[174:177], v[52:55]
	v_mfma_f32_16x16x32_bf16 v[44:47], v[144:147], v[188:191], v[44:47]
	v_mfma_f32_16x16x32_bf16 v[36:39], v[166:169], v[188:191], v[36:39]
	v_mfma_f32_16x16x32_bf16 v[28:31], v[144:147], v[204:207], v[28:31]
	v_mfma_f32_16x16x32_bf16 v[20:23], v[166:169], v[204:207], v[20:23]
	v_mfma_f32_16x16x32_bf16 v[12:15], v[144:147], v[212:215], v[12:15]
	v_mfma_f32_16x16x32_bf16 v[4:7], v[166:169], v[212:215], v[4:7]
	v_mfma_f32_16x16x32_bf16 v[60:63], v[148:151], v[178:181], v[60:63]
	v_mfma_f32_16x16x32_bf16 v[52:55], v[170:173], v[178:181], v[52:55]
	v_mfma_f32_16x16x32_bf16 v[44:47], v[148:151], v[192:195], v[44:47]
	v_mfma_f32_16x16x32_bf16 v[36:39], v[170:173], v[192:195], v[36:39]
	v_mfma_f32_16x16x32_bf16 v[28:31], v[148:151], v[208:211], v[28:31]
	v_mfma_f32_16x16x32_bf16 v[20:23], v[170:173], v[208:211], v[20:23]
	v_mfma_f32_16x16x32_bf16 v[12:15], v[148:151], v[216:219], v[12:15]
	v_mfma_f32_16x16x32_bf16 v[4:7], v[170:173], v[216:219], v[4:7]
	s_setprio 0
	s_barrier
	s_add_i32 s50, s50, 2
	s_add_u32 s40, s40, 0x100
	s_addc_u32 s41, s41, 0
	s_add_u32 s48, s48, 0x100
	s_addc_u32 s49, s49, 0
	s_cmp_gt_u32 s50, 13
	s_cbranch_scc0 .LBB0_140
	s_and_b64 vcc, exec, s[18:19]
	s_cbranch_vccz .LBB0_143
	s_barrier

.LBB0_403:
	s_andn2_b64 vcc, exec, s[12:13]
	s_cbranch_vccnz .LBB0_567
	v_bfe_i32 v2, v12, 27, 1
	v_lshlrev_b32_e32 v0, 4, v12
	v_lshrrev_b32_e32 v2, 22, v2
	v_add_u32_e32 v2, v0, v2
	v_and_b32_e32 v2, 0xfffffc00, v2
	v_sub_u32_e32 v2, v0, v2
	s_waitcnt lgkmcnt(0)
	v_ashrrev_i32_e32 v1, 31, v12
	v_lshrrev_b32_e32 v3, 4, v2
	v_lshrrev_b32_e32 v1, 26, v1
	v_bitop3_b32 v2, v3, v2, 32 bitop3:0x6c
	v_add_u32_e32 v1, v12, v1
	v_ashrrev_i32_e32 v4, 31, v2
	v_ashrrev_i32_e32 v1, 6, v1
	v_lshrrev_b32_e32 v4, 26, v4
	v_lshlrev_b32_e32 v3, 3, v1
	v_add_u32_e32 v4, v2, v4
	v_and_b32_e32 v3, -16, v3
	v_ashrrev_i32_e32 v5, 6, v4
	v_lshlrev_b32_e32 v1, 5, v1
	v_add_u32_e32 v3, v5, v3
	v_and_b32_e32 v13, 32, v1
	v_and_b32_e32 v1, 0xc0, v4
	v_sub_u32_e32 v1, v2, v1
	v_lshlrev_b32_e32 v2, 1, v3
	v_lshrrev_b32_e32 v4, 2, v3
	v_and_b32_e32 v5, 3, v5
	s_mov_b32 s12, 0x7fffffe0
	v_ashrrev_i16_sdwa v1, v223, sext(v1) dst_sel:DWORD dst_unused:UNUSED_PAD src0_sel:DWORD src1_sel:BYTE_0
	v_and_b32_e32 v2, 24, v2
	v_and_b32_e32 v4, 4, v4
	v_and_or_b32 v5, v3, s12, v5
	v_bfe_i32 v14, v1, 0, 16
	v_or3_b32 v2, v5, v4, v2
	v_add_u32_e32 v1, v13, v14
	v_mul_lo_u32 v15, v3, s11
	v_mul_lo_u32 v2, v2, s2
	v_add_u32_e32 v0, 0x2000, v0
	s_waitcnt vmcnt(0)
	v_add_lshl_u32 v154, v1, v15, 1
	v_add_lshl_u32 v156, v2, v1, 1
	v_ashrrev_i32_e32 v1, 31, v0
	v_lshrrev_b32_e32 v1, 22, v1
	v_add_u32_e32 v1, v0, v1
	v_ashrrev_i32_e32 v1, 10, v1
	v_mul_i32_i24_e32 v2, 0x400, v1
	v_sub_u32_e32 v0, v0, v2
	v_lshrrev_b32_e32 v2, 4, v0
	v_bitop3_b32 v0, v2, v0, 32 bitop3:0x6c
	v_ashrrev_i32_e32 v3, 31, v0
	v_lshrrev_b32_e32 v3, 26, v3
	v_lshlrev_b32_e32 v2, 3, v1
	v_add_u32_e32 v3, v0, v3
	v_and_b32_e32 v2, -16, v2
	v_ashrrev_i32_e32 v4, 6, v3
	s_ashr_i32 s42, s33, 6
	v_add_u32_e32 v2, v4, v2
	v_lshlrev_b32_e32 v1, 5, v1
	v_and_b32_e32 v4, 3, v4
	s_lshl_b32 s95, s2, 9
	v_and_b32_e32 v16, 32, v1
	v_and_b32_e32 v1, 0xc0, v3
	v_and_or_b32 v4, v2, s12, v4
	s_ashr_i32 s43, s33, 8
	s_lshl_b32 s12, s11, 8
	s_lshl_b32 s23, s2, 8
	s_lshl_b32 s31, s11, 9
	s_lshl_b32 s14, s42, 10
	s_mul_i32 s26, s95, s62
	v_sub_u32_e32 v0, v0, v1
	v_lshlrev_b32_e32 v1, 1, v2
	v_lshrrev_b32_e32 v3, 2, v2
	s_mul_hi_i32 s15, s95, s62
	s_add_u32 s52, s24, s26
	v_ashrrev_i16_sdwa v0, v223, sext(v0) dst_sel:DWORD dst_unused:UNUSED_PAD src0_sel:DWORD src1_sel:BYTE_0
	v_and_b32_e32 v1, 24, v1
	v_and_b32_e32 v3, 4, v3
	s_addc_u32 s53, s25, s15
	s_add_i32 s15, s14, 0
	v_bfe_i32 v17, v0, 0, 16
	v_or3_b32 v1, v4, v3, v1
	s_add_i32 m0, s15, 0x10000
	v_add_u32_e32 v0, v16, v17
	v_mul_lo_u32 v1, v1, s2
	global_load_lds_dwordx4 v156, s[52:53]
	s_add_i32 m0, s15, 0x12000
	v_add_lshl_u32 v160, v1, v0, 1
	s_add_u32 s26, s52, s23
	global_load_lds_dwordx4 v160, s[52:53]
	s_addc_u32 s27, s53, 0
	s_add_i32 m0, s15, 0x14000
	s_mul_i32 s28, s31, s36
	global_load_lds_dwordx4 v156, s[26:27]
	s_add_i32 m0, s15, 0x16000
	v_mul_lo_u32 v18, v2, s11
	s_mul_hi_i32 s11, s31, s36
	s_add_u32 s54, s96, s28
	v_mov_b32_e32 v157, v197
	v_mov_b32_e32 v161, v197
	s_addc_u32 s55, s97, s11
	s_add_i32 s59, s15, 0x2000
	v_lshl_add_u64 v[4:5], s[26:27], 0, v[156:157]
	v_lshl_add_u64 v[6:7], s[26:27], 0, v[160:161]
	global_load_lds_dwordx4 v160, s[26:27]
	s_mov_b32 m0, s15
	s_add_u32 s26, s54, s12
	v_add_lshl_u32 v158, v0, v18, 1
	global_load_lds_dwordx4 v154, s[54:55]
	s_mov_b32 m0, s59
	s_addc_u32 s27, s55, 0
	s_add_i32 s28, s15, 0x4000
	global_load_lds_dwordx4 v158, s[54:55]
	s_mov_b32 m0, s28
	s_add_i32 s29, s15, 0x6000
	global_load_lds_dwordx4 v154, s[26:27]
	s_mov_b32 m0, s29
	v_mov_b32_e32 v155, v197
	global_load_lds_dwordx4 v158, s[26:27]
	v_mov_b32_e32 v159, v197
	s_cmp_eq_u32 s43, 1
	v_writelane_b32 v249, s44, 62
	s_mov_b32 s13, s37
	v_lshl_add_u64 v[0:1], s[52:53], 0, v[156:157]
	v_lshl_add_u64 v[2:3], s[52:53], 0, v[160:161]
	v_lshl_add_u64 v[8:9], s[54:55], 0, v[154:155]
	v_lshl_add_u64 v[10:11], s[54:55], 0, v[158:159]
	s_cselect_b64 s[26:27], -1, 0
	s_cmp_lg_u32 s43, 1
	v_writelane_b32 v249, s26, 63
	s_nop 1
	v_writelane_b32 v248, s27, 0
	s_add_i32 m0, s15, 0x18000
	v_lshl_add_u64 v[0:1], v[0:1], 0, s[88:89]
	global_load_lds_dwordx4 v[0:1], off
	v_lshl_add_u64 v[0:1], v[2:3], 0, s[88:89]
	s_add_i32 m0, s15, 0x1a000
	s_add_i32 s26, s15, 0x8000
	global_load_lds_dwordx4 v[0:1], off
	v_lshl_add_u64 v[0:1], v[8:9], 0, s[88:89]
	s_mov_b32 m0, s26
	s_add_i32 s27, s15, 0xa000
	global_load_lds_dwordx4 v[0:1], off
	v_lshl_add_u64 v[0:1], v[10:11], 0, s[88:89]
	s_mov_b32 m0, s27
	s_nop 0
	global_load_lds_dwordx4 v[0:1], off
	s_add_i32 m0, s15, 0x1c000
	v_lshl_add_u64 v[0:1], v[4:5], 0, s[88:89]
	global_load_lds_dwordx4 v[0:1], off
	v_lshl_add_u64 v[0:1], v[6:7], 0, s[88:89]
	s_add_i32 m0, s15, 0x1e000
	s_nop 0
	global_load_lds_dwordx4 v[0:1], off
	s_cmp_lg_u32 s43, 1
	s_cbranch_scc1 .LBB0_406
	s_barrier
.LBB0_406:
	s_waitcnt vmcnt(8)
	s_barrier
	v_and_b32_e32 v2, 15, v12
	v_lshlrev_b32_e32 v4, 2, v12
	v_bfe_u32 v1, v12, 4, 2
	v_lshlrev_b32_e32 v0, 4, v1
	s_and_b32 s11, s42, 3
	s_lshr_b32 s91, s2, 6
	v_lshl_or_b32 v194, s43, 6, v2
	v_lshl_or_b32 v2, v2, 6, v0
	s_lshl_b32 s2, s43, 13
	v_and_b32_e32 v4, 32, v4
	v_bitop3_b32 v5, v2, s2, v4 bitop3:0xde
	s_lshl_b32 s2, s11, 12
	s_add_i32 s99, s91, -2
	v_lshlrev_b32_e32 v3, 3, v1
	v_bitop3_b32 v195, v2, s2, v4 bitop3:0xde
	s_cmpk_lt_u32 s33, 0x100
	v_lshlrev_b32_e32 v2, 2, v1
	v_cmp_gt_u32_e64 s[42:43], 2, v1
	v_cmp_eq_u32_e64 s[44:45], 0, v1
	v_lshlrev_b32_e32 v1, 1, v12
	s_cselect_b64 s[80:81], -1, 0
	v_and_b32_e32 v196, 32, v1
	s_lshl_b32 s93, s46, 2
	v_mov_b32_e32 v1, v197
	v_lshl_add_u64 v[166:167], s[8:9], 0, v[0:1]
	v_cvt_f32_ubyte0_e32 v0, s93
	v_rcp_iflag_f32_e32 v0, v0
	s_lshl_b32 s2, s46, 3
	v_readlane_b32 s50, v251, 13
	s_cmp_eq_u32 s11, 0
	v_mul_f32_e32 v0, 0x4f7ffffe, v0
	v_cvt_u32_f32_e32 v0, v0
	v_readlane_b32 s51, v251, 14
	s_cselect_b64 s[8:9], -1, 0
	s_and_b64 s[8:9], s[48:49], s[8:9]
	v_lshl_add_u64 v[162:163], s[50:51], 0, v[196:197]
	v_readlane_b32 s50, v251, 15
	v_readlane_b32 s51, v251, 16
	s_or_b64 s[82:83], s[34:35], s[8:9]
	s_sub_i32 s8, 0, s93
	v_readfirstlane_b32 s9, v0
	v_add_u32_e32 v0, v15, v13
	v_lshl_add_u64 v[164:165], s[50:51], 0, v[196:197]
	s_mul_i32 s8, s8, s9
	v_add_lshl_u32 v196, v0, v14, 1
	v_add_u32_e32 v0, v18, v16
	s_mul_hi_u32 s8, s9, s8
	v_lshl_add_u64 v[168:169], s[12:13], 0, v[196:197]
	v_add_lshl_u32 v196, v0, v17, 1
	s_mov_b32 s33, 0
	s_mov_b32 s77, s37
	v_cmp_gt_u32_e64 s[46:47], s19, v2
	s_mov_b32 s19, s18
	v_lshl_or_b32 v204, s11, 5, v3
	s_add_i32 s94, s9, s8
	v_lshl_add_u64 v[170:171], s[12:13], 0, v[196:197]
	v_add_u32_e32 v205, 0, v5
	s_branch .LBB0_409

.LBB0_415:
	s_add_u32 s50, s54, 0x80
	s_addc_u32 s51, s55, 0
	s_add_u32 s54, s52, 0x100
	v_mov_b32_e32 v228, 0
	v_mov_b32_e32 v229, 0
	v_mov_b32_e32 v230, 0
	v_mov_b32_e32 v231, 0
	s_addc_u32 s55, s53, 0
	s_mov_b32 s52, 0
	v_mfma_f32_32x32x16_bf16 v[0:15], v[228:231], v[228:231], 0
	v_mfma_f32_32x32x16_bf16 v[16:31], v[228:231], v[228:231], 0
	v_mfma_f32_32x32x16_bf16 v[32:47], v[228:231], v[228:231], 0
	v_mfma_f32_32x32x16_bf16 v[48:63], v[228:231], v[228:231], 0
	v_mfma_f32_32x32x16_bf16 v[64:79], v[228:231], v[228:231], 0
	v_mfma_f32_32x32x16_bf16 v[80:95], v[228:231], v[228:231], 0
	v_mfma_f32_32x32x16_bf16 v[96:111], v[228:231], v[228:231], 0
	v_mfma_f32_32x32x16_bf16 v[112:127], v[228:231], v[228:231], 0
	s_cmp_lg_u32 s33, 1
	s_cbranch_scc1 .Lfw_1
	s_waitcnt vmcnt(6)
	s_barrier
.Lfw_1:
.LBB0_416:
	s_add_i32 s56, s52, 2
	s_add_u32 s57, s50, 0x80
	s_addc_u32 s53, s51, 0
	s_add_i32 s63, 0, 0x10000
	s_cmp_eq_u32 s99, s52
	s_cselect_b32 s53, s9, s53
	s_cselect_b32 s52, s8, s57
	s_cselect_b32 s61, s85, s55
	s_cselect_b32 s60, s84, s54
	s_add_i32 s57, 0, 0x14000
	v_add_u32_e32 v140, s63, v195
	v_add_u32_e32 v152, s57, v195
	ds_read_b128 v[128:131], v140
	ds_read_b128 v[132:135], v140 offset:1024
	ds_read_b128 v[136:139], v140 offset:2048
	ds_read_b128 v[140:143], v140 offset:3072
	ds_read_b128 v[144:147], v152
	ds_read_b128 v[148:151], v152 offset:1024
	ds_read_b128 v[172:175], v152 offset:2048
	ds_read_b128 v[176:179], v152 offset:3072
	v_lshl_add_u64 v[152:153], s[50:51], 0, v[168:169]
	s_add_i32 m0, s15, 0xc000
	ds_read_b128 v[180:183], v205
	ds_read_b128 v[184:187], v205 offset:1024
	ds_read_b128 v[188:191], v205 offset:2048
	ds_read_b128 v[206:209], v205 offset:3072
	ds_read_b128 v[210:213], v205 offset:4096
	ds_read_b128 v[214:217], v205 offset:5120
	ds_read_b128 v[218:221], v205 offset:6144
	ds_read_b128 v[226:229], v205 offset:7168
	global_load_lds_dwordx4 v[152:153], off
	v_lshl_add_u64 v[152:153], s[50:51], 0, v[170:171]
	s_add_i32 m0, s15, 0xe000
	s_nop 0
	global_load_lds_dwordx4 v[152:153], off
	s_waitcnt vmcnt(8)
	s_waitcnt lgkmcnt(0)
	s_barrier
	s_setprio 1
	s_waitcnt lgkmcnt(0)
	v_mfma_f32_16x16x32_bf16 v[124:127], v[128:131], v[180:183], v[124:127]
	v_mfma_f32_16x16x32_bf16 v[120:123], v[136:139], v[180:183], v[120:123]
	v_mfma_f32_16x16x32_bf16 v[116:119], v[128:131], v[188:191], v[116:119]
	v_mfma_f32_16x16x32_bf16 v[112:115], v[136:139], v[188:191], v[112:115]
	v_mfma_f32_16x16x32_bf16 v[108:111], v[128:131], v[210:213], v[108:111]
	v_mfma_f32_16x16x32_bf16 v[104:107], v[136:139], v[210:213], v[104:107]
	v_mfma_f32_16x16x32_bf16 v[100:103], v[128:131], v[218:221], v[100:103]
	v_mfma_f32_16x16x32_bf16 v[96:99], v[136:139], v[218:221], v[96:99]
	v_mfma_f32_16x16x32_bf16 v[124:127], v[132:135], v[184:187], v[124:127]
	v_mfma_f32_16x16x32_bf16 v[120:123], v[140:143], v[184:187], v[120:123]
	v_mfma_f32_16x16x32_bf16 v[116:119], v[132:135], v[206:209], v[116:119]
	v_mfma_f32_16x16x32_bf16 v[112:115], v[140:143], v[206:209], v[112:115]
	v_mfma_f32_16x16x32_bf16 v[108:111], v[132:135], v[214:217], v[108:111]
	v_mfma_f32_16x16x32_bf16 v[104:107], v[140:143], v[214:217], v[104:107]
	v_mfma_f32_16x16x32_bf16 v[100:103], v[132:135], v[226:229], v[100:103]
	v_mfma_f32_16x16x32_bf16 v[96:99], v[140:143], v[226:229], v[96:99]
	s_setprio 0
	s_setprio 1
	v_mfma_f32_16x16x32_bf16 v[60:63], v[144:147], v[180:183], v[60:63]
	v_mfma_f32_16x16x32_bf16 v[56:59], v[172:175], v[180:183], v[56:59]
	v_mfma_f32_16x16x32_bf16 v[52:55], v[144:147], v[188:191], v[52:55]
	v_mfma_f32_16x16x32_bf16 v[48:51], v[172:175], v[188:191], v[48:51]
	v_mfma_f32_16x16x32_bf16 v[44:47], v[144:147], v[210:213], v[44:47]
	v_mfma_f32_16x16x32_bf16 v[40:43], v[172:175], v[210:213], v[40:43]
	v_mfma_f32_16x16x32_bf16 v[36:39], v[144:147], v[218:221], v[36:39]
	v_mfma_f32_16x16x32_bf16 v[32:35], v[172:175], v[218:221], v[32:35]
	v_mfma_f32_16x16x32_bf16 v[60:63], v[148:151], v[184:187], v[60:63]
	v_mfma_f32_16x16x32_bf16 v[56:59], v[176:179], v[184:187], v[56:59]
	v_mfma_f32_16x16x32_bf16 v[52:55], v[148:151], v[206:209], v[52:55]
	v_mfma_f32_16x16x32_bf16 v[48:51], v[176:179], v[206:209], v[48:51]
	v_mfma_f32_16x16x32_bf16 v[44:47], v[148:151], v[214:217], v[44:47]
	v_mfma_f32_16x16x32_bf16 v[40:43], v[176:179], v[214:217], v[40:43]
	v_mfma_f32_16x16x32_bf16 v[36:39], v[148:151], v[226:229], v[36:39]
	v_mfma_f32_16x16x32_bf16 v[32:35], v[176:179], v[226:229], v[32:35]
	s_setprio 0
	s_barrier
	s_add_i32 s63, s63, s14
	v_lshl_add_u64 v[152:153], s[60:61], 0, v[156:157]
	s_mov_b32 m0, s63
	ds_read_b128 v[180:183], v205 offset:16384
	ds_read_b128 v[184:187], v205 offset:17408
	ds_read_b128 v[188:191], v205 offset:18432
	ds_read_b128 v[206:209], v205 offset:19456
	ds_read_b128 v[210:213], v205 offset:20480
	ds_read_b128 v[214:217], v205 offset:21504
	ds_read_b128 v[218:221], v205 offset:22528
	ds_read_b128 v[226:229], v205 offset:23552
	global_load_lds_dwordx4 v[152:153], off
	s_add_i32 m0, s63, 0x2000
	v_lshl_add_u64 v[192:193], s[60:61], 0, v[160:161]
	s_add_u32 s60, s60, s23
	s_addc_u32 s61, s61, 0
	s_add_i32 s57, s57, s14
	global_load_lds_dwordx4 v[192:193], off
	v_lshl_add_u64 v[230:231], s[60:61], 0, v[156:157]
	s_mov_b32 m0, s57
	v_lshl_add_u64 v[232:233], s[60:61], 0, v[160:161]
	global_load_lds_dwordx4 v[230:231], off
	s_add_i32 m0, s57, 0x2000
	v_lshl_add_u64 v[234:235], s[52:53], 0, v[154:155]
	global_load_lds_dwordx4 v[232:233], off
	s_mov_b32 m0, s15
	v_lshl_add_u64 v[236:237], s[52:53], 0, v[158:159]
	global_load_lds_dwordx4 v[234:235], off
	s_mov_b32 m0, s59
	s_nop 0
	global_load_lds_dwordx4 v[236:237], off
	s_waitcnt vmcnt(8)
	s_waitcnt lgkmcnt(0)
	s_barrier
	s_setprio 1
	s_waitcnt lgkmcnt(0)
	v_mfma_f32_16x16x32_bf16 v[92:95], v[128:131], v[180:183], v[92:95]
	v_mfma_f32_16x16x32_bf16 v[88:91], v[136:139], v[180:183], v[88:91]
	v_mfma_f32_16x16x32_bf16 v[84:87], v[128:131], v[188:191], v[84:87]
	v_mfma_f32_16x16x32_bf16 v[80:83], v[136:139], v[188:191], v[80:83]
	v_mfma_f32_16x16x32_bf16 v[76:79], v[128:131], v[210:213], v[76:79]
	v_mfma_f32_16x16x32_bf16 v[72:75], v[136:139], v[210:213], v[72:75]
	v_mfma_f32_16x16x32_bf16 v[68:71], v[128:131], v[218:221], v[68:71]
	v_mfma_f32_16x16x32_bf16 v[64:67], v[136:139], v[218:221], v[64:67]
	v_mfma_f32_16x16x32_bf16 v[92:95], v[132:135], v[184:187], v[92:95]
	v_mfma_f32_16x16x32_bf16 v[88:91], v[140:143], v[184:187], v[88:91]
	v_mfma_f32_16x16x32_bf16 v[84:87], v[132:135], v[206:209], v[84:87]
	v_mfma_f32_16x16x32_bf16 v[80:83], v[140:143], v[206:209], v[80:83]
	v_mfma_f32_16x16x32_bf16 v[76:79], v[132:135], v[214:217], v[76:79]
	v_mfma_f32_16x16x32_bf16 v[72:75], v[140:143], v[214:217], v[72:75]
	v_mfma_f32_16x16x32_bf16 v[68:71], v[132:135], v[226:229], v[68:71]
	v_mfma_f32_16x16x32_bf16 v[64:67], v[140:143], v[226:229], v[64:67]
	s_setprio 0
	s_setprio 1
	v_mfma_f32_16x16x32_bf16 v[28:31], v[144:147], v[180:183], v[28:31]
	v_mfma_f32_16x16x32_bf16 v[24:27], v[172:175], v[180:183], v[24:27]
	v_mfma_f32_16x16x32_bf16 v[20:23], v[144:147], v[188:191], v[20:23]
	v_mfma_f32_16x16x32_bf16 v[16:19], v[172:175], v[188:191], v[16:19]
	v_mfma_f32_16x16x32_bf16 v[12:15], v[144:147], v[210:213], v[12:15]
	v_mfma_f32_16x16x32_bf16 v[8:11], v[172:175], v[210:213], v[8:11]
	v_mfma_f32_16x16x32_bf16 v[4:7], v[144:147], v[218:221], v[4:7]
	v_mfma_f32_16x16x32_bf16 v[0:3], v[172:175], v[218:221], v[0:3]
	v_mfma_f32_16x16x32_bf16 v[28:31], v[148:151], v[184:187], v[28:31]
	v_mfma_f32_16x16x32_bf16 v[24:27], v[176:179], v[184:187], v[24:27]
	v_mfma_f32_16x16x32_bf16 v[20:23], v[148:151], v[206:209], v[20:23]
	v_mfma_f32_16x16x32_bf16 v[16:19], v[176:179], v[206:209], v[16:19]
	v_mfma_f32_16x16x32_bf16 v[12:15], v[148:151], v[214:217], v[12:15]
	v_mfma_f32_16x16x32_bf16 v[8:11], v[176:179], v[214:217], v[8:11]
	v_mfma_f32_16x16x32_bf16 v[4:7], v[148:151], v[226:229], v[4:7]
	v_mfma_f32_16x16x32_bf16 v[0:3], v[176:179], v[226:229], v[0:3]
	s_setprio 0
	s_barrier
	s_add_i32 s57, 0, 0x18000
	s_add_i32 s60, 0, 0x1c000
	v_add_u32_e32 v140, s57, v195
	v_add_u32_e32 v176, s60, v195
	ds_read_b128 v[128:131], v140
	ds_read_b128 v[132:135], v140 offset:1024
	ds_read_b128 v[136:139], v140 offset:2048
	ds_read_b128 v[140:143], v140 offset:3072
	ds_read_b128 v[144:147], v176
	ds_read_b128 v[148:151], v176 offset:1024
	ds_read_b128 v[172:175], v176 offset:2048
	ds_read_b128 v[176:179], v176 offset:3072
	s_add_u32 s52, s52, s12
	s_addc_u32 s53, s53, 0
	s_mov_b32 m0, s28
	v_lshl_add_u64 v[238:239], s[52:53], 0, v[154:155]
	ds_read_b128 v[180:183], v205 offset:32768
	ds_read_b128 v[184:187], v205 offset:33792
	ds_read_b128 v[188:191], v205 offset:34816
	ds_read_b128 v[206:209], v205 offset:35840
	ds_read_b128 v[210:213], v205 offset:36864
	ds_read_b128 v[214:217], v205 offset:37888
	ds_read_b128 v[218:221], v205 offset:38912
	ds_read_b128 v[226:229], v205 offset:39936
	global_load_lds_dwordx4 v[238:239], off
	v_lshl_add_u64 v[238:239], s[52:53], 0, v[158:159]
	s_mov_b32 m0, s29
	s_nop 0
	global_load_lds_dwordx4 v[238:239], off
	s_waitcnt vmcnt(8)
	s_waitcnt lgkmcnt(0)
	s_barrier
	s_setprio 1
	s_waitcnt lgkmcnt(0)
	v_mfma_f32_16x16x32_bf16 v[124:127], v[128:131], v[180:183], v[124:127]
	v_mfma_f32_16x16x32_bf16 v[120:123], v[136:139], v[180:183], v[120:123]
	v_mfma_f32_16x16x32_bf16 v[116:119], v[128:131], v[188:191], v[116:119]
	v_mfma_f32_16x16x32_bf16 v[112:115], v[136:139], v[188:191], v[112:115]
	v_mfma_f32_16x16x32_bf16 v[108:111], v[128:131], v[210:213], v[108:111]
	v_mfma_f32_16x16x32_bf16 v[104:107], v[136:139], v[210:213], v[104:107]
	v_mfma_f32_16x16x32_bf16 v[100:103], v[128:131], v[218:221], v[100:103]
	v_mfma_f32_16x16x32_bf16 v[96:99], v[136:139], v[218:221], v[96:99]
	v_mfma_f32_16x16x32_bf16 v[124:127], v[132:135], v[184:187], v[124:127]
	v_mfma_f32_16x16x32_bf16 v[120:123], v[140:143], v[184:187], v[120:123]
	v_mfma_f32_16x16x32_bf16 v[116:119], v[132:135], v[206:209], v[116:119]
	v_mfma_f32_16x16x32_bf16 v[112:115], v[140:143], v[206:209], v[112:115]
	v_mfma_f32_16x16x32_bf16 v[108:111], v[132:135], v[214:217], v[108:111]
	v_mfma_f32_16x16x32_bf16 v[104:107], v[140:143], v[214:217], v[104:107]
	v_mfma_f32_16x16x32_bf16 v[100:103], v[132:135], v[226:229], v[100:103]
	v_mfma_f32_16x16x32_bf16 v[96:99], v[140:143], v[226:229], v[96:99]
	s_setprio 0
	s_setprio 1
	v_mfma_f32_16x16x32_bf16 v[60:63], v[144:147], v[180:183], v[60:63]
	v_mfma_f32_16x16x32_bf16 v[56:59], v[172:175], v[180:183], v[56:59]
	v_mfma_f32_16x16x32_bf16 v[52:55], v[144:147], v[188:191], v[52:55]
	v_mfma_f32_16x16x32_bf16 v[48:51], v[172:175], v[188:191], v[48:51]
	v_mfma_f32_16x16x32_bf16 v[44:47], v[144:147], v[210:213], v[44:47]
	v_mfma_f32_16x16x32_bf16 v[40:43], v[172:175], v[210:213], v[40:43]
	v_mfma_f32_16x16x32_bf16 v[36:39], v[144:147], v[218:221], v[36:39]
	v_mfma_f32_16x16x32_bf16 v[32:35], v[172:175], v[218:221], v[32:35]
	v_mfma_f32_16x16x32_bf16 v[60:63], v[148:151], v[184:187], v[60:63]
	v_mfma_f32_16x16x32_bf16 v[56:59], v[176:179], v[184:187], v[56:59]
	v_mfma_f32_16x16x32_bf16 v[52:55], v[148:151], v[206:209], v[52:55]
	v_mfma_f32_16x16x32_bf16 v[48:51], v[176:179], v[206:209], v[48:51]
	v_mfma_f32_16x16x32_bf16 v[44:47], v[148:151], v[214:217], v[44:47]
	v_mfma_f32_16x16x32_bf16 v[40:43], v[176:179], v[214:217], v[40:43]
	v_mfma_f32_16x16x32_bf16 v[36:39], v[148:151], v[226:229], v[36:39]
	v_mfma_f32_16x16x32_bf16 v[32:35], v[176:179], v[226:229], v[32:35]
	s_setprio 0
	s_barrier
	s_add_i32 s52, s57, s14
	v_lshl_add_u64 v[152:153], v[152:153], 0, s[88:89]
	s_mov_b32 m0, s52
	ds_read_b128 v[180:183], v205 offset:49152
	ds_read_b128 v[184:187], v205 offset:50176
	ds_read_b128 v[188:191], v205 offset:51200
	ds_read_b128 v[206:209], v205 offset:52224
	ds_read_b128 v[210:213], v205 offset:53248
	ds_read_b128 v[214:217], v205 offset:54272
	ds_read_b128 v[218:221], v205 offset:55296
	ds_read_b128 v[226:229], v205 offset:56320
	global_load_lds_dwordx4 v[152:153], off
	v_lshl_add_u64 v[152:153], v[192:193], 0, s[88:89]
	s_add_i32 m0, s52, 0x2000
	s_add_i32 s52, s60, s14
	global_load_lds_dwordx4 v[152:153], off
	v_lshl_add_u64 v[152:153], v[230:231], 0, s[88:89]
	s_mov_b32 m0, s52
	s_nop 0
	global_load_lds_dwordx4 v[152:153], off
	v_lshl_add_u64 v[152:153], v[232:233], 0, s[88:89]
	s_add_i32 m0, s52, 0x2000
	s_nop 0
	global_load_lds_dwordx4 v[152:153], off
	v_lshl_add_u64 v[152:153], v[234:235], 0, s[88:89]
	s_mov_b32 m0, s26
	s_nop 0
	global_load_lds_dwordx4 v[152:153], off
	v_lshl_add_u64 v[152:153], v[236:237], 0, s[88:89]
	s_mov_b32 m0, s27
	s_nop 0
	global_load_lds_dwordx4 v[152:153], off
	s_waitcnt vmcnt(8)
	s_waitcnt lgkmcnt(0)
	s_barrier
	s_setprio 1
	s_waitcnt lgkmcnt(0)
	v_mfma_f32_16x16x32_bf16 v[92:95], v[128:131], v[180:183], v[92:95]
	v_mfma_f32_16x16x32_bf16 v[88:91], v[136:139], v[180:183], v[88:91]
	v_mfma_f32_16x16x32_bf16 v[84:87], v[128:131], v[188:191], v[84:87]
	v_mfma_f32_16x16x32_bf16 v[80:83], v[136:139], v[188:191], v[80:83]
	v_mfma_f32_16x16x32_bf16 v[76:79], v[128:131], v[210:213], v[76:79]
	v_mfma_f32_16x16x32_bf16 v[72:75], v[136:139], v[210:213], v[72:75]
	v_mfma_f32_16x16x32_bf16 v[68:71], v[128:131], v[218:221], v[68:71]
	v_mfma_f32_16x16x32_bf16 v[64:67], v[136:139], v[218:221], v[64:67]
	v_mfma_f32_16x16x32_bf16 v[92:95], v[132:135], v[184:187], v[92:95]
	v_mfma_f32_16x16x32_bf16 v[88:91], v[140:143], v[184:187], v[88:91]
	v_mfma_f32_16x16x32_bf16 v[84:87], v[132:135], v[206:209], v[84:87]
	v_mfma_f32_16x16x32_bf16 v[80:83], v[140:143], v[206:209], v[80:83]
	v_mfma_f32_16x16x32_bf16 v[76:79], v[132:135], v[214:217], v[76:79]
	v_mfma_f32_16x16x32_bf16 v[72:75], v[140:143], v[214:217], v[72:75]
	v_mfma_f32_16x16x32_bf16 v[68:71], v[132:135], v[226:229], v[68:71]
	v_mfma_f32_16x16x32_bf16 v[64:67], v[140:143], v[226:229], v[64:67]
	s_setprio 0
	s_setprio 1
	v_mfma_f32_16x16x32_bf16 v[28:31], v[144:147], v[180:183], v[28:31]
	v_mfma_f32_16x16x32_bf16 v[24:27], v[172:175], v[180:183], v[24:27]
	v_mfma_f32_16x16x32_bf16 v[20:23], v[144:147], v[188:191], v[20:23]
	v_mfma_f32_16x16x32_bf16 v[16:19], v[172:175], v[188:191], v[16:19]
	v_mfma_f32_16x16x32_bf16 v[12:15], v[144:147], v[210:213], v[12:15]
	v_mfma_f32_16x16x32_bf16 v[8:11], v[172:175], v[210:213], v[8:11]
	v_mfma_f32_16x16x32_bf16 v[4:7], v[144:147], v[218:221], v[4:7]
	v_mfma_f32_16x16x32_bf16 v[0:3], v[172:175], v[218:221], v[0:3]
	v_mfma_f32_16x16x32_bf16 v[28:31], v[148:151], v[184:187], v[28:31]
	v_mfma_f32_16x16x32_bf16 v[24:27], v[176:179], v[184:187], v[24:27]
	v_mfma_f32_16x16x32_bf16 v[20:23], v[148:151], v[206:209], v[20:23]
	v_mfma_f32_16x16x32_bf16 v[16:19], v[176:179], v[206:209], v[16:19]
	v_mfma_f32_16x16x32_bf16 v[12:15], v[148:151], v[214:217], v[12:15]
	v_mfma_f32_16x16x32_bf16 v[8:11], v[176:179], v[214:217], v[8:11]
	v_mfma_f32_16x16x32_bf16 v[4:7], v[148:151], v[226:229], v[4:7]
	v_mfma_f32_16x16x32_bf16 v[0:3], v[176:179], v[226:229], v[0:3]
	s_setprio 0
	s_barrier
	s_add_u32 s50, s50, 0x100
	s_addc_u32 s51, s51, 0
	s_add_u32 s54, s54, 0x100
	s_addc_u32 s55, s55, 0
	s_cmp_ge_u32 s56, s91
	s_mov_b32 s52, s56
	s_cbranch_scc0 .LBB0_416
	s_and_b64 vcc, exec, s[80:81]
	s_cbranch_vccz .LBB0_419
	s_barrier

.LBB0_838:
	v_readlane_b32 s12, v252, 57
	v_mov_b32_e32 v18, v199
	v_readlane_b32 s13, v252, 58
	s_andn2_b64 vcc, exec, s[12:13]
	v_readfirstlane_b32 s22, v18
	s_cbranch_vccnz .LBB0_878
	v_lshlrev_b32_e32 v0, 4, v18
	s_waitcnt lgkmcnt(0)
	v_add_u32_e32 v1, 0x2000, v0
	v_ashrrev_i32_e32 v2, 31, v1
	v_lshrrev_b32_e32 v2, 22, v2
	v_add_u32_e32 v2, v1, v2
	v_ashrrev_i32_e32 v2, 10, v2
	v_mul_i32_i24_e32 v3, 0x400, v2
	v_sub_u32_e32 v1, v1, v3
	v_lshrrev_b32_e32 v3, 4, v1
	v_bitop3_b32 v1, v3, v1, 32 bitop3:0x6c
	v_ashrrev_i32_e32 v3, 31, v1
	v_lshrrev_b32_e32 v3, 26, v3
	v_add_u32_e32 v3, v1, v3
	v_lshlrev_b32_e32 v5, 3, v2
	v_ashrrev_i32_e32 v4, 6, v3
	v_and_b32_e32 v5, -16, v5
	v_lshlrev_b32_e32 v2, 5, v2
	v_add_u32_e32 v5, v4, v5
	v_and_b32_e32 v12, 32, v2
	v_and_b32_e32 v2, 0xc0, v3
	v_and_b32_e32 v4, 3, v4
	s_mov_b32 s14, 0x7fffffe0
	v_lshrrev_b32_e32 v6, 2, v5
	v_lshlrev_b32_e32 v7, 1, v5
	v_sub_u32_e32 v1, v1, v2
	v_and_or_b32 v4, v5, s14, v4
	v_and_b32_e32 v6, 4, v6
	v_and_b32_e32 v7, 24, v7
	v_ashrrev_i16_sdwa v1, v223, sext(v1) dst_sel:DWORD dst_unused:UNUSED_PAD src0_sel:DWORD src1_sel:BYTE_0
	v_or3_b32 v4, v4, v6, v7
	v_bfe_i32 v13, v1, 0, 16
	v_mul_lo_u32 v4, v4, s20
	v_add_u32_e32 v1, v12, v13
	v_mul_lo_u32 v14, v5, s20
	v_add_lshl_u32 v128, v4, v1, 1
	v_add_lshl_u32 v130, v1, v14, 1
	v_bfe_i32 v1, v18, 27, 1
	v_lshrrev_b32_e32 v1, 22, v1
	v_add_u32_e32 v1, v0, v1
	v_and_b32_e32 v1, 0xfffffc00, v1
	v_sub_u32_e32 v0, v0, v1
	v_lshrrev_b32_e32 v1, 4, v0
	v_ashrrev_i32_e32 v3, 31, v18
	v_bitop3_b32 v0, v1, v0, 32 bitop3:0x6c
	v_lshrrev_b32_e32 v3, 26, v3
	v_ashrrev_i32_e32 v1, 31, v0
	v_add_u32_e32 v3, v18, v3
	v_lshrrev_b32_e32 v1, 26, v1
	v_ashrrev_i32_e32 v3, 6, v3
	v_add_u32_e32 v1, v0, v1
	v_lshlrev_b32_e32 v4, 3, v3
	v_ashrrev_i32_e32 v2, 6, v1
	v_and_b32_e32 v4, -16, v4
	v_add_u32_e32 v4, v2, v4
	v_and_b32_e32 v2, 3, v2
	v_and_b32_e32 v1, 0xc0, v1
	s_ashr_i32 s23, s22, 6
	s_lshl_b32 s3, s20, 9
	v_and_or_b32 v2, v4, s14, v2
	v_lshrrev_b32_e32 v5, 2, v4
	v_lshlrev_b32_e32 v6, 1, v4
	v_sub_u32_e32 v0, v0, v1
	v_readlane_b32 s14, v250, 8
	v_readlane_b32 s18, v250, 10
	s_ashr_i32 s21, s22, 8
	s_lshl_b32 s12, s20, 8
	s_lshl_b32 s11, s23, 10
	v_and_b32_e32 v5, 4, v5
	v_and_b32_e32 v6, 24, v6
	v_lshlrev_b32_e32 v3, 5, v3
	v_ashrrev_i16_sdwa v0, v223, sext(v0) dst_sel:DWORD dst_unused:UNUSED_PAD src0_sel:DWORD src1_sel:BYTE_0
	s_mul_hi_i32 s15, s3, s14
	s_mul_i32 s17, s3, s14
	s_mul_hi_i32 s14, s3, s18
	s_mul_i32 s18, s3, s18
	v_or3_b32 v2, v2, v5, v6
	v_and_b32_e32 v15, 32, v3
	v_bfe_i32 v16, v0, 0, 16
	s_add_u32 s46, s6, s18
	v_mul_lo_u32 v2, v2, s20
	v_add_u32_e32 v0, v15, v16
	s_addc_u32 s47, s7, s14
	s_add_i32 s14, s11, 0
	v_add_lshl_u32 v196, v2, v0, 1
	s_add_i32 m0, s14, 0x10000
	v_readlane_b32 s19, v250, 11
	s_waitcnt vmcnt(0)
	global_load_lds_dwordx4 v196, s[46:47]
	s_add_i32 m0, s14, 0x12000
	s_add_u32 s18, s46, s12
	global_load_lds_dwordx4 v128, s[46:47]
	s_addc_u32 s19, s47, 0
	s_add_i32 m0, s14, 0x14000
	v_mul_lo_u32 v17, v4, s20
	global_load_lds_dwordx4 v196, s[18:19]
	s_add_i32 m0, s14, 0x16000
	s_add_u32 s34, s8, s17
	v_mov_b32_e32 v129, v197
	s_addc_u32 s35, s9, s15
	s_add_i32 s15, s14, 0x2000
	v_add_lshl_u32 v132, v0, v17, 1
	v_lshl_add_u64 v[4:5], s[18:19], 0, v[196:197]
	v_lshl_add_u64 v[6:7], s[18:19], 0, v[128:129]
	global_load_lds_dwordx4 v128, s[18:19]
	s_mov_b32 m0, s14
	s_add_u32 s18, s34, s12
	global_load_lds_dwordx4 v132, s[34:35]
	s_mov_b32 m0, s15
	s_addc_u32 s19, s35, 0
	s_add_i32 s17, s14, 0x4000
	global_load_lds_dwordx4 v130, s[34:35]
	s_mov_b32 m0, s17
	s_add_i32 s26, s14, 0x6000
	global_load_lds_dwordx4 v132, s[18:19]
	s_mov_b32 m0, s26
	v_mov_b32_e32 v133, v197
	global_load_lds_dwordx4 v130, s[18:19]
	v_mov_b32_e32 v131, v197
	s_cmp_eq_u32 s21, 1
	s_mov_b32 s60, s30
	s_mov_b32 s13, s37
	v_lshl_add_u64 v[0:1], s[46:47], 0, v[196:197]
	v_lshl_add_u64 v[2:3], s[46:47], 0, v[128:129]
	v_lshl_add_u64 v[8:9], s[34:35], 0, v[132:133]
	v_lshl_add_u64 v[10:11], s[34:35], 0, v[130:131]
	s_cselect_b64 s[18:19], -1, 0
	s_cmp_lg_u32 s21, 1
	s_add_i32 m0, s14, 0x18000
	v_lshl_add_u64 v[0:1], v[0:1], 0, s[88:89]
	global_load_lds_dwordx4 v[0:1], off
	v_lshl_add_u64 v[0:1], v[2:3], 0, s[88:89]
	s_add_i32 m0, s14, 0x1a000
	s_add_i32 s29, s14, 0x8000
	global_load_lds_dwordx4 v[0:1], off
	v_lshl_add_u64 v[0:1], v[8:9], 0, s[88:89]
	s_mov_b32 m0, s29
	s_add_i32 s33, s14, 0xa000
	global_load_lds_dwordx4 v[0:1], off
	v_lshl_add_u64 v[0:1], v[10:11], 0, s[88:89]
	s_mov_b32 m0, s33
	s_nop 0
	global_load_lds_dwordx4 v[0:1], off
	s_add_i32 m0, s14, 0x1c000
	v_lshl_add_u64 v[0:1], v[4:5], 0, s[88:89]
	global_load_lds_dwordx4 v[0:1], off
	v_lshl_add_u64 v[0:1], v[6:7], 0, s[88:89]
	s_add_i32 m0, s14, 0x1e000
	s_nop 0
	global_load_lds_dwordx4 v[0:1], off
	s_cmp_lg_u32 s21, 1
	s_cbranch_scc1 .LBB0_841
	s_barrier
.LBB0_841:
	v_bfe_u32 v19, v18, 4, 2
	v_and_b32_e32 v20, 15, v18
	v_lshlrev_b32_e32 v22, 4, v19
	v_lshlrev_b32_e32 v18, 2, v18
	s_and_b32 s27, s23, 3
	s_lshr_b32 s28, s20, 6
	v_lshl_or_b32 v144, s21, 6, v20
	v_lshl_or_b32 v20, v20, 6, v22
	s_lshl_b32 s20, s21, 13
	v_and_b32_e32 v18, 32, v18
	v_bitop3_b32 v22, v20, s20, v18 bitop3:0xde
	s_lshl_b32 s20, s27, 12
	v_bitop3_b32 v145, v20, s20, v18 bitop3:0xde
	v_readlane_b32 s20, v249, 56
	v_readlane_b32 s21, v249, 57
	s_add_u32 s20, s20, 0x100000
	s_addc_u32 s21, s21, 0
	s_waitcnt vmcnt(8)
	s_barrier
	s_add_i32 s48, s28, -2
	v_lshlrev_b32_e32 v21, 3, v19
	v_add_u32_e32 v0, v17, v15
	v_add_lshl_u32 v0, v0, v16, 1
	v_mov_b32_e32 v1, v197
	v_lshl_add_u64 v[134:135], s[12:13], 0, v[0:1]
	v_add_u32_e32 v0, v14, v12
	s_cmpk_lt_u32 s22, 0x100
	v_add_lshl_u32 v0, v0, v13, 1
	v_lshl_or_b32 v146, s27, 5, v21
	s_cselect_b64 s[22:23], -1, 0
	s_mov_b32 s49, 0
	v_cmp_eq_u32_e64 s[40:41], 0, v19
	v_lshl_add_u64 v[136:137], s[12:13], 0, v[0:1]
	v_add_u32_e32 v147, 0, v22
	v_readlane_b32 s36, v250, 9
	v_readlane_b32 s51, v250, 8
	s_branch .LBB0_844

.LBB0_854:
	s_add_u32 s34, s34, 0x80
	s_addc_u32 s35, s35, 0
	s_add_u32 s46, s46, 0x100
	v_mov_b32_e32 v228, 0
	v_mov_b32_e32 v229, 0
	v_mov_b32_e32 v230, 0
	v_mov_b32_e32 v231, 0
	s_addc_u32 s47, s47, 0
	s_mov_b32 s44, 0
	s_waitcnt lgkmcnt(0)
	v_mfma_f32_32x32x16_bf16 v[0:15], v[228:231], v[228:231], 0
	v_mfma_f32_32x32x16_bf16 v[16:31], v[228:231], v[228:231], 0
	v_mfma_f32_32x32x16_bf16 v[32:47], v[228:231], v[228:231], 0
	v_mfma_f32_32x32x16_bf16 v[48:63], v[228:231], v[228:231], 0
	v_mfma_f32_32x32x16_bf16 v[64:79], v[228:231], v[228:231], 0
	v_mfma_f32_32x32x16_bf16 v[80:95], v[228:231], v[228:231], 0
	v_mfma_f32_32x32x16_bf16 v[96:111], v[228:231], v[228:231], 0
	v_mfma_f32_32x32x16_bf16 v[112:127], v[228:231], v[228:231], 0
	s_cmp_lg_u32 s49, 1
	s_cbranch_scc1 .Lfw_2
	s_waitcnt vmcnt(6)
	s_barrier
.Lfw_2:
.LBB0_855:
	s_add_i32 s52, s44, 2
	s_add_u32 s53, s34, 0x80
	s_addc_u32 s45, s35, 0
	s_add_i32 s56, 0, 0x10000
	s_cmp_eq_u32 s48, s44
	s_cselect_b32 s45, s25, s45
	s_cselect_b32 s44, s24, s53
	v_add_u32_e32 v142, s56, v145
	s_cselect_b32 s55, s31, s47
	s_cselect_b32 s54, s30, s46
	s_add_i32 s53, 0, 0x14000
	ds_read_b128 v[138:141], v142
	ds_read_b128 v[148:151], v142 offset:1024
	ds_read_b128 v[152:155], v142 offset:2048
	ds_read_b128 v[156:159], v142 offset:3072
	v_add_u32_e32 v142, s53, v145
	ds_read_b128 v[160:163], v142
	ds_read_b128 v[164:167], v142 offset:1024
	ds_read_b128 v[168:171], v142 offset:2048
	ds_read_b128 v[172:175], v142 offset:3072
	v_lshl_add_u64 v[142:143], s[34:35], 0, v[134:135]
	s_add_i32 m0, s14, 0xc000
	ds_read_b128 v[176:179], v147
	ds_read_b128 v[180:183], v147 offset:1024
	ds_read_b128 v[184:187], v147 offset:2048
	ds_read_b128 v[188:191], v147 offset:3072
	ds_read_b128 v[192:195], v147 offset:4096
	ds_read_b128 v[204:207], v147 offset:5120
	ds_read_b128 v[208:211], v147 offset:6144
	ds_read_b128 v[212:215], v147 offset:7168
	global_load_lds_dwordx4 v[142:143], off
	v_lshl_add_u64 v[142:143], s[34:35], 0, v[136:137]
	s_add_i32 m0, s14, 0xe000
	s_nop 0
	global_load_lds_dwordx4 v[142:143], off
	s_waitcnt vmcnt(8)
	s_waitcnt lgkmcnt(0)
	s_barrier
	s_setprio 1
	s_waitcnt lgkmcnt(0)
	v_mfma_f32_16x16x32_bf16 v[124:127], v[138:141], v[176:179], v[124:127]
	v_mfma_f32_16x16x32_bf16 v[120:123], v[152:155], v[176:179], v[120:123]
	v_mfma_f32_16x16x32_bf16 v[108:111], v[138:141], v[184:187], v[108:111]
	v_mfma_f32_16x16x32_bf16 v[104:107], v[152:155], v[184:187], v[104:107]
	v_mfma_f32_16x16x32_bf16 v[92:95], v[138:141], v[192:195], v[92:95]
	v_mfma_f32_16x16x32_bf16 v[88:91], v[152:155], v[192:195], v[88:91]
	v_mfma_f32_16x16x32_bf16 v[76:79], v[138:141], v[208:211], v[76:79]
	v_mfma_f32_16x16x32_bf16 v[72:75], v[152:155], v[208:211], v[72:75]
	v_mfma_f32_16x16x32_bf16 v[124:127], v[148:151], v[180:183], v[124:127]
	v_mfma_f32_16x16x32_bf16 v[120:123], v[156:159], v[180:183], v[120:123]
	v_mfma_f32_16x16x32_bf16 v[108:111], v[148:151], v[188:191], v[108:111]
	v_mfma_f32_16x16x32_bf16 v[104:107], v[156:159], v[188:191], v[104:107]
	v_mfma_f32_16x16x32_bf16 v[92:95], v[148:151], v[204:207], v[92:95]
	v_mfma_f32_16x16x32_bf16 v[88:91], v[156:159], v[204:207], v[88:91]
	v_mfma_f32_16x16x32_bf16 v[76:79], v[148:151], v[212:215], v[76:79]
	v_mfma_f32_16x16x32_bf16 v[72:75], v[156:159], v[212:215], v[72:75]
	s_setprio 0
	s_setprio 1
	v_mfma_f32_16x16x32_bf16 v[116:119], v[160:163], v[176:179], v[116:119]
	v_mfma_f32_16x16x32_bf16 v[112:115], v[168:171], v[176:179], v[112:115]
	v_mfma_f32_16x16x32_bf16 v[100:103], v[160:163], v[184:187], v[100:103]
	v_mfma_f32_16x16x32_bf16 v[96:99], v[168:171], v[184:187], v[96:99]
	v_mfma_f32_16x16x32_bf16 v[84:87], v[160:163], v[192:195], v[84:87]
	v_mfma_f32_16x16x32_bf16 v[80:83], v[168:171], v[192:195], v[80:83]
	v_mfma_f32_16x16x32_bf16 v[68:71], v[160:163], v[208:211], v[68:71]
	v_mfma_f32_16x16x32_bf16 v[64:67], v[168:171], v[208:211], v[64:67]
	v_mfma_f32_16x16x32_bf16 v[116:119], v[164:167], v[180:183], v[116:119]
	v_mfma_f32_16x16x32_bf16 v[112:115], v[172:175], v[180:183], v[112:115]
	v_mfma_f32_16x16x32_bf16 v[100:103], v[164:167], v[188:191], v[100:103]
	v_mfma_f32_16x16x32_bf16 v[96:99], v[172:175], v[188:191], v[96:99]
	v_mfma_f32_16x16x32_bf16 v[84:87], v[164:167], v[204:207], v[84:87]
	v_mfma_f32_16x16x32_bf16 v[80:83], v[172:175], v[204:207], v[80:83]
	v_mfma_f32_16x16x32_bf16 v[68:71], v[164:167], v[212:215], v[68:71]
	v_mfma_f32_16x16x32_bf16 v[64:67], v[172:175], v[212:215], v[64:67]
	s_setprio 0
	s_barrier
	s_add_i32 s56, s56, s11
	v_lshl_add_u64 v[142:143], s[54:55], 0, v[196:197]
	s_mov_b32 m0, s56
	ds_read_b128 v[176:179], v147 offset:16384
	ds_read_b128 v[180:183], v147 offset:17408
	ds_read_b128 v[184:187], v147 offset:18432
	ds_read_b128 v[188:191], v147 offset:19456
	ds_read_b128 v[192:195], v147 offset:20480
	ds_read_b128 v[204:207], v147 offset:21504
	ds_read_b128 v[208:211], v147 offset:22528
	ds_read_b128 v[212:215], v147 offset:23552
	global_load_lds_dwordx4 v[142:143], off
	s_add_i32 m0, s56, 0x2000
	v_lshl_add_u64 v[216:217], s[54:55], 0, v[128:129]
	s_add_u32 s54, s54, s12
	s_addc_u32 s55, s55, 0
	s_add_i32 s53, s53, s11
	global_load_lds_dwordx4 v[216:217], off
	v_lshl_add_u64 v[218:219], s[54:55], 0, v[196:197]
	s_mov_b32 m0, s53
	v_lshl_add_u64 v[220:221], s[54:55], 0, v[128:129]
	global_load_lds_dwordx4 v[218:219], off
	s_add_i32 m0, s53, 0x2000
	v_lshl_add_u64 v[226:227], s[44:45], 0, v[132:133]
	global_load_lds_dwordx4 v[220:221], off
	s_mov_b32 m0, s14
	v_lshl_add_u64 v[228:229], s[44:45], 0, v[130:131]
	global_load_lds_dwordx4 v[226:227], off
	s_mov_b32 m0, s15
	s_nop 0
	global_load_lds_dwordx4 v[228:229], off
	s_waitcnt vmcnt(8)
	s_waitcnt lgkmcnt(0)
	s_barrier
	s_setprio 1
	s_waitcnt lgkmcnt(0)
	v_mfma_f32_16x16x32_bf16 v[60:63], v[138:141], v[176:179], v[60:63]
	v_mfma_f32_16x16x32_bf16 v[56:59], v[152:155], v[176:179], v[56:59]
	v_mfma_f32_16x16x32_bf16 v[44:47], v[138:141], v[184:187], v[44:47]
	v_mfma_f32_16x16x32_bf16 v[40:43], v[152:155], v[184:187], v[40:43]
	v_mfma_f32_16x16x32_bf16 v[28:31], v[138:141], v[192:195], v[28:31]
	v_mfma_f32_16x16x32_bf16 v[24:27], v[152:155], v[192:195], v[24:27]
	v_mfma_f32_16x16x32_bf16 v[12:15], v[138:141], v[208:211], v[12:15]
	v_mfma_f32_16x16x32_bf16 v[8:11], v[152:155], v[208:211], v[8:11]
	v_mfma_f32_16x16x32_bf16 v[60:63], v[148:151], v[180:183], v[60:63]
	v_mfma_f32_16x16x32_bf16 v[56:59], v[156:159], v[180:183], v[56:59]
	v_mfma_f32_16x16x32_bf16 v[44:47], v[148:151], v[188:191], v[44:47]
	v_mfma_f32_16x16x32_bf16 v[40:43], v[156:159], v[188:191], v[40:43]
	v_mfma_f32_16x16x32_bf16 v[28:31], v[148:151], v[204:207], v[28:31]
	v_mfma_f32_16x16x32_bf16 v[24:27], v[156:159], v[204:207], v[24:27]
	v_mfma_f32_16x16x32_bf16 v[12:15], v[148:151], v[212:215], v[12:15]
	v_mfma_f32_16x16x32_bf16 v[8:11], v[156:159], v[212:215], v[8:11]
	s_setprio 0
	s_setprio 1
	v_mfma_f32_16x16x32_bf16 v[52:55], v[160:163], v[176:179], v[52:55]
	v_mfma_f32_16x16x32_bf16 v[48:51], v[168:171], v[176:179], v[48:51]
	v_mfma_f32_16x16x32_bf16 v[36:39], v[160:163], v[184:187], v[36:39]
	v_mfma_f32_16x16x32_bf16 v[32:35], v[168:171], v[184:187], v[32:35]
	v_mfma_f32_16x16x32_bf16 v[20:23], v[160:163], v[192:195], v[20:23]
	v_mfma_f32_16x16x32_bf16 v[16:19], v[168:171], v[192:195], v[16:19]
	v_mfma_f32_16x16x32_bf16 v[4:7], v[160:163], v[208:211], v[4:7]
	v_mfma_f32_16x16x32_bf16 v[0:3], v[168:171], v[208:211], v[0:3]
	v_mfma_f32_16x16x32_bf16 v[52:55], v[164:167], v[180:183], v[52:55]
	v_mfma_f32_16x16x32_bf16 v[48:51], v[172:175], v[180:183], v[48:51]
	v_mfma_f32_16x16x32_bf16 v[36:39], v[164:167], v[188:191], v[36:39]
	v_mfma_f32_16x16x32_bf16 v[32:35], v[172:175], v[188:191], v[32:35]
	v_mfma_f32_16x16x32_bf16 v[20:23], v[164:167], v[204:207], v[20:23]
	v_mfma_f32_16x16x32_bf16 v[16:19], v[172:175], v[204:207], v[16:19]
	v_mfma_f32_16x16x32_bf16 v[4:7], v[164:167], v[212:215], v[4:7]
	v_mfma_f32_16x16x32_bf16 v[0:3], v[172:175], v[212:215], v[0:3]
	s_setprio 0
	s_barrier
	s_add_i32 s53, 0, 0x18000
	s_add_i32 s54, 0, 0x1c000
	v_add_u32_e32 v156, s53, v145
	v_add_u32_e32 v172, s54, v145
	ds_read_b128 v[138:141], v156
	ds_read_b128 v[148:151], v156 offset:1024
	ds_read_b128 v[152:155], v156 offset:2048
	ds_read_b128 v[156:159], v156 offset:3072
	ds_read_b128 v[160:163], v172
	ds_read_b128 v[164:167], v172 offset:1024
	ds_read_b128 v[168:171], v172 offset:2048
	ds_read_b128 v[172:175], v172 offset:3072
	s_add_u32 s44, s44, s12
	s_addc_u32 s45, s45, 0
	s_mov_b32 m0, s17
	v_lshl_add_u64 v[230:231], s[44:45], 0, v[132:133]
	ds_read_b128 v[176:179], v147 offset:32768
	ds_read_b128 v[180:183], v147 offset:33792
	ds_read_b128 v[184:187], v147 offset:34816
	ds_read_b128 v[188:191], v147 offset:35840
	ds_read_b128 v[192:195], v147 offset:36864
	ds_read_b128 v[204:207], v147 offset:37888
	ds_read_b128 v[208:211], v147 offset:38912
	ds_read_b128 v[212:215], v147 offset:39936
	global_load_lds_dwordx4 v[230:231], off
	v_lshl_add_u64 v[230:231], s[44:45], 0, v[130:131]
	s_mov_b32 m0, s26
	s_nop 0
	global_load_lds_dwordx4 v[230:231], off
	s_waitcnt vmcnt(8)
	s_waitcnt lgkmcnt(0)
	s_barrier
	s_setprio 1
	s_waitcnt lgkmcnt(0)
	v_mfma_f32_16x16x32_bf16 v[124:127], v[138:141], v[176:179], v[124:127]
	v_mfma_f32_16x16x32_bf16 v[120:123], v[152:155], v[176:179], v[120:123]
	v_mfma_f32_16x16x32_bf16 v[108:111], v[138:141], v[184:187], v[108:111]
	v_mfma_f32_16x16x32_bf16 v[104:107], v[152:155], v[184:187], v[104:107]
	v_mfma_f32_16x16x32_bf16 v[92:95], v[138:141], v[192:195], v[92:95]
	v_mfma_f32_16x16x32_bf16 v[88:91], v[152:155], v[192:195], v[88:91]
	v_mfma_f32_16x16x32_bf16 v[76:79], v[138:141], v[208:211], v[76:79]
	v_mfma_f32_16x16x32_bf16 v[72:75], v[152:155], v[208:211], v[72:75]
	v_mfma_f32_16x16x32_bf16 v[124:127], v[148:151], v[180:183], v[124:127]
	v_mfma_f32_16x16x32_bf16 v[120:123], v[156:159], v[180:183], v[120:123]
	v_mfma_f32_16x16x32_bf16 v[108:111], v[148:151], v[188:191], v[108:111]
	v_mfma_f32_16x16x32_bf16 v[104:107], v[156:159], v[188:191], v[104:107]
	v_mfma_f32_16x16x32_bf16 v[92:95], v[148:151], v[204:207], v[92:95]
	v_mfma_f32_16x16x32_bf16 v[88:91], v[156:159], v[204:207], v[88:91]
	v_mfma_f32_16x16x32_bf16 v[76:79], v[148:151], v[212:215], v[76:79]
	v_mfma_f32_16x16x32_bf16 v[72:75], v[156:159], v[212:215], v[72:75]
	s_setprio 0
	s_setprio 1
	v_mfma_f32_16x16x32_bf16 v[116:119], v[160:163], v[176:179], v[116:119]
	v_mfma_f32_16x16x32_bf16 v[112:115], v[168:171], v[176:179], v[112:115]
	v_mfma_f32_16x16x32_bf16 v[100:103], v[160:163], v[184:187], v[100:103]
	v_mfma_f32_16x16x32_bf16 v[96:99], v[168:171], v[184:187], v[96:99]
	v_mfma_f32_16x16x32_bf16 v[84:87], v[160:163], v[192:195], v[84:87]
	v_mfma_f32_16x16x32_bf16 v[80:83], v[168:171], v[192:195], v[80:83]
	v_mfma_f32_16x16x32_bf16 v[68:71], v[160:163], v[208:211], v[68:71]
	v_mfma_f32_16x16x32_bf16 v[64:67], v[168:171], v[208:211], v[64:67]
	v_mfma_f32_16x16x32_bf16 v[116:119], v[164:167], v[180:183], v[116:119]
	v_mfma_f32_16x16x32_bf16 v[112:115], v[172:175], v[180:183], v[112:115]
	v_mfma_f32_16x16x32_bf16 v[100:103], v[164:167], v[188:191], v[100:103]
	v_mfma_f32_16x16x32_bf16 v[96:99], v[172:175], v[188:191], v[96:99]
	v_mfma_f32_16x16x32_bf16 v[84:87], v[164:167], v[204:207], v[84:87]
	v_mfma_f32_16x16x32_bf16 v[80:83], v[172:175], v[204:207], v[80:83]
	v_mfma_f32_16x16x32_bf16 v[68:71], v[164:167], v[212:215], v[68:71]
	v_mfma_f32_16x16x32_bf16 v[64:67], v[172:175], v[212:215], v[64:67]
	s_setprio 0
	s_barrier
	s_add_i32 s44, s53, s11
	v_lshl_add_u64 v[142:143], v[142:143], 0, s[88:89]
	s_mov_b32 m0, s44
	ds_read_b128 v[176:179], v147 offset:49152
	ds_read_b128 v[180:183], v147 offset:50176
	ds_read_b128 v[184:187], v147 offset:51200
	ds_read_b128 v[188:191], v147 offset:52224
	ds_read_b128 v[192:195], v147 offset:53248
	ds_read_b128 v[204:207], v147 offset:54272
	ds_read_b128 v[208:211], v147 offset:55296
	ds_read_b128 v[212:215], v147 offset:56320
	global_load_lds_dwordx4 v[142:143], off
	v_lshl_add_u64 v[142:143], v[216:217], 0, s[88:89]
	s_add_i32 m0, s44, 0x2000
	s_add_i32 s44, s54, s11
	global_load_lds_dwordx4 v[142:143], off
	v_lshl_add_u64 v[142:143], v[218:219], 0, s[88:89]
	s_mov_b32 m0, s44
	s_nop 0
	global_load_lds_dwordx4 v[142:143], off
	v_lshl_add_u64 v[142:143], v[220:221], 0, s[88:89]
	s_add_i32 m0, s44, 0x2000
	s_nop 0
	global_load_lds_dwordx4 v[142:143], off
	v_lshl_add_u64 v[142:143], v[226:227], 0, s[88:89]
	s_mov_b32 m0, s29
	s_nop 0
	global_load_lds_dwordx4 v[142:143], off
	v_lshl_add_u64 v[142:143], v[228:229], 0, s[88:89]
	s_mov_b32 m0, s33
	s_nop 0
	global_load_lds_dwordx4 v[142:143], off
	s_waitcnt vmcnt(8)
	s_waitcnt lgkmcnt(0)
	s_barrier
	s_setprio 1
	s_waitcnt lgkmcnt(0)
	v_mfma_f32_16x16x32_bf16 v[60:63], v[138:141], v[176:179], v[60:63]
	v_mfma_f32_16x16x32_bf16 v[56:59], v[152:155], v[176:179], v[56:59]
	v_mfma_f32_16x16x32_bf16 v[44:47], v[138:141], v[184:187], v[44:47]
	v_mfma_f32_16x16x32_bf16 v[40:43], v[152:155], v[184:187], v[40:43]
	v_mfma_f32_16x16x32_bf16 v[28:31], v[138:141], v[192:195], v[28:31]
	v_mfma_f32_16x16x32_bf16 v[24:27], v[152:155], v[192:195], v[24:27]
	v_mfma_f32_16x16x32_bf16 v[12:15], v[138:141], v[208:211], v[12:15]
	v_mfma_f32_16x16x32_bf16 v[8:11], v[152:155], v[208:211], v[8:11]
	v_mfma_f32_16x16x32_bf16 v[60:63], v[148:151], v[180:183], v[60:63]
	v_mfma_f32_16x16x32_bf16 v[56:59], v[156:159], v[180:183], v[56:59]
	v_mfma_f32_16x16x32_bf16 v[44:47], v[148:151], v[188:191], v[44:47]
	v_mfma_f32_16x16x32_bf16 v[40:43], v[156:159], v[188:191], v[40:43]
	v_mfma_f32_16x16x32_bf16 v[28:31], v[148:151], v[204:207], v[28:31]
	v_mfma_f32_16x16x32_bf16 v[24:27], v[156:159], v[204:207], v[24:27]
	v_mfma_f32_16x16x32_bf16 v[12:15], v[148:151], v[212:215], v[12:15]
	v_mfma_f32_16x16x32_bf16 v[8:11], v[156:159], v[212:215], v[8:11]
	s_setprio 0
	s_setprio 1
	v_mfma_f32_16x16x32_bf16 v[52:55], v[160:163], v[176:179], v[52:55]
	v_mfma_f32_16x16x32_bf16 v[48:51], v[168:171], v[176:179], v[48:51]
	v_mfma_f32_16x16x32_bf16 v[36:39], v[160:163], v[184:187], v[36:39]
	v_mfma_f32_16x16x32_bf16 v[32:35], v[168:171], v[184:187], v[32:35]
	v_mfma_f32_16x16x32_bf16 v[20:23], v[160:163], v[192:195], v[20:23]
	v_mfma_f32_16x16x32_bf16 v[16:19], v[168:171], v[192:195], v[16:19]
	v_mfma_f32_16x16x32_bf16 v[4:7], v[160:163], v[208:211], v[4:7]
	v_mfma_f32_16x16x32_bf16 v[0:3], v[168:171], v[208:211], v[0:3]
	v_mfma_f32_16x16x32_bf16 v[52:55], v[164:167], v[180:183], v[52:55]
	v_mfma_f32_16x16x32_bf16 v[48:51], v[172:175], v[180:183], v[48:51]
	v_mfma_f32_16x16x32_bf16 v[36:39], v[164:167], v[188:191], v[36:39]
	v_mfma_f32_16x16x32_bf16 v[32:35], v[172:175], v[188:191], v[32:35]
	v_mfma_f32_16x16x32_bf16 v[20:23], v[164:167], v[204:207], v[20:23]
	v_mfma_f32_16x16x32_bf16 v[16:19], v[172:175], v[204:207], v[16:19]
	v_mfma_f32_16x16x32_bf16 v[4:7], v[164:167], v[212:215], v[4:7]
	v_mfma_f32_16x16x32_bf16 v[0:3], v[172:175], v[212:215], v[0:3]
	s_setprio 0
	s_barrier
	s_add_u32 s34, s34, 0x100
	s_addc_u32 s35, s35, 0
	s_add_u32 s46, s46, 0x100
	s_addc_u32 s47, s47, 0
	s_cmp_ge_u32 s52, s28
	s_mov_b32 s44, s52
	s_cbranch_scc0 .LBB0_855
	s_and_b64 vcc, exec, s[22:23]
	s_cbranch_vccz .LBB0_858
	s_barrier
